# per-XCD barriers also around cross attention (wq -> xattn -> wo), xattn units remapped to the XCD that owns their rows
# speedup vs baseline: 1.0085x; 1.0085x over previous
; #define LAS __attribute__((address_space(3)))
; #define DSEC(k) do { if (PROBE_DSEC) { const unsigned long long tn_ = __builtin_amdgcn_s_memrealtime(); if (PROBE_DSEC == (k)) tsec += tn_ - tl_; tl_ = tn_; } } while (0)
; #define XK_LOAD(R, b_, h_, hh_) do { _Pragma("unroll") for (int i = 0; i < 8; ++i) { const int p = tid + 512 * i, m = p >> 4, cb = p & 15; R[i] = *(const u32x4*)(memK + (size_t)((b_) * NMEM + m) * D + (h_) * 256 + 128 * (hh_) + 8 * cb); } } while (0)
; #define XK_WRITE(R) do { _Pragma("unroll") for (int i = 0; i < 8; ++i) { const int p = tid + 512 * i, m = p >> 4, cb = p & 15; *(LAS u32x4*)(KL + m * KSTR + 16 * cb) = R[i]; } } while (0)
; DI void xattn_phase(LAS unsigned char* L, const bf16* Qx, const bf16* memK, const bf16* memVT, bf16* Ox, int G, int bid, int tid, unsigned long long& tsec) {
;     unsigned long long tl_ = PROBE_DSEC ? __builtin_amdgcn_s_memrealtime() : 0;
;     const int wid = __builtin_amdgcn_readfirstlane(tid >> 6), lane = tid & 63, fr = lane & 15, fq = lane >> 4;
;     LAS unsigned char* KL = L; LAS unsigned char* VL = L + KL_BYTES;
;     u32x4 ra[8], rb[8];
;     if (bid < 512) { const int h0 = (bid >> 5) & 3, b0 = bid >> 7; XK_LOAD(ra, b0, h0, 0); XV_LOAD(rb, b0, h0, 0); }
;     for (int unit = bid; unit < 512; unit += G) {
;         const int j = unit & 31, h = (unit >> 5) & 3, b = unit >> 7;
;         const int nun = unit + G < 512 ? unit + G : unit, hn = (nun >> 5) & 3, bn = nun >> 7;
;         asm volatile("" : "+v"(ra[0]), "+v"(ra[1]), "+v"(ra[2]), "+v"(ra[3]), "+v"(ra[4]), "+v"(ra[5]), "+v"(ra[6]), "+v"(ra[7]));
;         asm volatile("" : "+v"(rb[0]), "+v"(rb[1]), "+v"(rb[2]), "+v"(rb[3]), "+v"(rb[4]), "+v"(rb[5]), "+v"(rb[6]), "+v"(rb[7]));
;         const int tok0 = b * T + 128 * j; const size_t tq = (size_t)(tok0 + 16 * wid + fr);
;         f32x4 s[16];
; #pragma unroll
;         for (int kt = 0; kt < 16; ++kt) s[kt] = (f32x4){0.f, 0.f, 0.f, 0.f};
; #pragma unroll
;         for (int hh = 0; hh < 2; ++hh) {
;             __syncthreads();
;             XK_WRITE(ra);
;             if (hh == 0) { XV_WRITE(rb); XK_LOAD(ra, b, h, 1); XV_LOAD(rb, b, h, 1); }
;             else XK_LOAD(ra, bn, hn, 0);
;             __syncthreads();
;             DSEC(11);
; #pragma unroll
;             for (int k4 = 0; k4 < 4; ++k4) { const bf16x8 qk = *(const bf16x8*)(Qx + tq * D + h * 256 + 128 * hh + 32 * k4 + 8 * fq);
.LBB0_1099:
	s_cmpk_gt_i32 s4, 0x1ff
	v_readfirstlane_b32 s5, v67
	s_cbranch_scc1 .LBB0_1102
	v_readlane_b32 s2, v254, 29
	v_readlane_b32 s3, v254, 30
	s_and_b64 s[2:3], s[2:3], exec
	s_brev_b32 s2, 40
	s_mov_b32 s3, 0x14200000
	s_cselect_b32 s2, s2, 0x14c00000
	s_cselect_b32 s3, s3, 0x14e00000
	s_add_u32 s6, s78, s0
	s_addc_u32 s7, s79, s1
	s_add_u32 s0, s6, 0x6400000
	s_addc_u32 s1, s7, 0
	s_add_u32 s36, s6, s2
	s_addc_u32 s37, s7, 0
	s_add_u32 s2, s6, s3
	s_addc_u32 s3, s7, 0
	s_add_u32 s38, s6, 0x8400000
	s_addc_u32 s39, s7, 0
	s_lshr_b32 s16, s5, 6
	s_lshl_b32 s49, s16, 13
	s_mov_b32 s48, 0x3d800000
	v_and_b32_e32 v236, 63, v67
	v_and_b32_e32 v237, 15, v236
	v_lshrrev_b32_e32 v248, 4, v236
	v_xor_b32_e32 v234, 16, v236
	v_lshlrev_b32_e32 v234, 2, v234
	v_xor_b32_e32 v235, 32, v236
	v_lshlrev_b32_e32 v235, 2, v235
	v_add_u32_e32 v249, 0, v248
	v_xor_b32_e32 v198, v237, v249
	v_lshl_add_u32 v249, s16, 5, v249
	v_lshlrev_b32_e32 v249, 11, v249
	v_lshl_add_u32 v198, v198, 4, v249
	v_add_u32_e32 v249, 4, v248
	v_xor_b32_e32 v199, v237, v249
	v_lshl_add_u32 v249, s16, 5, v249
	v_lshlrev_b32_e32 v249, 11, v249
	v_lshl_add_u32 v199, v199, 4, v249
	v_add_u32_e32 v249, 8, v248
	v_xor_b32_e32 v200, v237, v249
	v_lshl_add_u32 v249, s16, 5, v249
	v_lshlrev_b32_e32 v249, 11, v249
	v_lshl_add_u32 v200, v200, 4, v249
	v_add_u32_e32 v249, 12, v248
	v_xor_b32_e32 v201, v237, v249
	v_lshl_add_u32 v249, s16, 5, v249
	v_lshlrev_b32_e32 v249, 11, v249
	v_lshl_add_u32 v201, v201, 4, v249
	v_add_u32_e32 v249, 0, v248
	v_xor_b32_e32 v249, v249, v237
	v_lshlrev_b32_e32 v249, 4, v249
	v_lshl_add_u32 v206, v237, 8, v249
	v_add_u32_e32 v212, 0x10000, v206
	v_add_u32_e32 v249, 4, v248
	v_xor_b32_e32 v249, v249, v237
	v_lshlrev_b32_e32 v249, 4, v249
	v_lshl_add_u32 v207, v237, 8, v249
	v_add_u32_e32 v213, 0x10000, v207
	v_add_u32_e32 v249, 8, v248
	v_xor_b32_e32 v249, v249, v237
	v_lshlrev_b32_e32 v249, 4, v249
	v_lshl_add_u32 v208, v237, 8, v249
	v_add_u32_e32 v214, 0x10000, v208
	v_add_u32_e32 v249, 12, v248
	v_xor_b32_e32 v249, v249, v237
	v_lshlrev_b32_e32 v249, 4, v249
	v_lshl_add_u32 v209, v237, 8, v249
	v_add_u32_e32 v215, 0x10000, v209
	v_lshrrev_b32_e32 v0, 1, v248
	v_add_u32_e32 v249, 0, v0
	v_xor_b32_e32 v249, v249, v237
	v_lshlrev_b32_e32 v249, 4, v249
	v_lshl_add_u32 v216, v237, 9, v249
	v_add_u32_e32 v249, 2, v0
	v_xor_b32_e32 v249, v249, v237
	v_lshlrev_b32_e32 v249, 4, v249
	v_lshl_add_u32 v217, v237, 9, v249
	v_add_u32_e32 v249, 4, v0
	v_xor_b32_e32 v249, v249, v237
	v_lshlrev_b32_e32 v249, 4, v249
	v_lshl_add_u32 v218, v237, 9, v249
	v_add_u32_e32 v249, 6, v0
	v_xor_b32_e32 v249, v249, v237
	v_lshlrev_b32_e32 v249, 4, v249
	v_lshl_add_u32 v219, v237, 9, v249
	v_add_u32_e32 v249, 8, v0
	v_xor_b32_e32 v249, v249, v237
	v_lshlrev_b32_e32 v249, 4, v249
	v_lshl_add_u32 v220, v237, 9, v249
	v_add_u32_e32 v249, 10, v0
	v_xor_b32_e32 v249, v249, v237
	v_lshlrev_b32_e32 v249, 4, v249
	v_lshl_add_u32 v221, v237, 9, v249
	v_add_u32_e32 v249, 12, v0
	v_xor_b32_e32 v249, v249, v237
	v_lshlrev_b32_e32 v249, 4, v249
	v_lshl_add_u32 v222, v237, 9, v249
	v_add_u32_e32 v249, 14, v0
	v_xor_b32_e32 v249, v249, v237
	v_lshlrev_b32_e32 v249, 4, v249
	v_lshl_add_u32 v223, v237, 9, v249
	v_and_b32_e32 v249, 1, v248
	v_lshlrev_b32_e32 v249, 3, v249
	v_add_u32_e32 v216, v216, v249
	v_add_u32_e32 v224, 0x10000, v216
	v_add_u32_e32 v217, v217, v249
	v_add_u32_e32 v225, 0x10000, v217
	v_add_u32_e32 v218, v218, v249
	v_add_u32_e32 v226, 0x10000, v218
	v_add_u32_e32 v219, v219, v249
	v_add_u32_e32 v227, 0x10000, v219
	v_add_u32_e32 v220, v220, v249
	v_add_u32_e32 v228, 0x10000, v220
	v_add_u32_e32 v221, v221, v249
	v_add_u32_e32 v229, 0x10000, v221
	v_add_u32_e32 v222, v222, v249
	v_add_u32_e32 v230, 0x10000, v222
	v_add_u32_e32 v223, v223, v249
	v_add_u32_e32 v231, 0x10000, v223
	v_lshl_add_u32 v249, s16, 4, v237
	v_lshlrev_b32_e32 v249, 11, v249
	v_lshl_add_u32 v232, v248, 4, v249
	v_lshl_add_u32 v233, v248, 3, v249
	v_readlane_b32 s44, v252, 0
	s_nop 3
	s_and_b32 s45, s44, 7
	s_lshr_b32 s46, s44, 3
	s_and_b32 s47, s45, 1
	s_lshl_b32 s47, s47, 4
	s_and_b32 s17, s46, 15
	s_or_b32 s17, s17, s47
	s_lshr_b32 s47, s46, 4
	s_lshl_b32 s47, s47, 6
	s_or_b32 s17, s17, s47
	s_lshr_b32 s47, s45, 1
	s_lshl_b32 s47, s47, 7
	s_or_b32 s17, s17, s47
	s_and_b32 s44, s17, 31
	s_bfe_u32 s45, s17, 0x20005
	s_lshr_b32 s46, s17, 7
	s_lshl_b32 s47, s46, 12
	s_lshl_b32 s44, s44, 7
	s_add_u32 s47, s47, s44
	s_lshl_b32 s47, s47, 11
	s_lshl_b32 s44, s45, 9
	s_add_u32 s47, s47, s44
	s_add_u32 s20, s0, s47
	s_addc_u32 s21, s1, 0
	s_add_u32 s22, s38, s47
	s_addc_u32 s23, s39, 0
	s_lshl_b32 s47, s46, 19
	s_add_u32 s47, s47, s44
	s_add_u32 s24, s36, s47
	s_addc_u32 s25, s37, 0
	s_lshl_b32 s47, s45, 19
	s_lshl_b32 s44, s46, 9
	s_add_u32 s47, s47, s44
	s_add_u32 s42, s2, s47
	s_addc_u32 s43, s3, 0
	s_add_u32 s44, s24, 0
	s_addc_u32 s45, s25, 0
	s_add_u32 s46, s44, 0x8000
	s_addc_u32 s47, s45, 0
	s_add_u32 m0, s49, 0
	s_nop 0
	global_load_lds_dwordx4 v198, s[44:45]
	s_add_u32 m0, s49, 1024
	s_nop 0
	global_load_lds_dwordx4 v199, s[44:45]
	s_add_u32 m0, s49, 2048
	s_nop 0
	global_load_lds_dwordx4 v200, s[44:45]
	s_add_u32 m0, s49, 3072
	s_nop 0
	global_load_lds_dwordx4 v201, s[44:45]
	s_add_u32 m0, s49, 4096
	s_nop 0
	global_load_lds_dwordx4 v198, s[46:47]
	s_add_u32 m0, s49, 5120
	s_nop 0
	global_load_lds_dwordx4 v199, s[46:47]
	s_add_u32 m0, s49, 6144
	s_nop 0
	global_load_lds_dwordx4 v200, s[46:47]
	s_add_u32 m0, s49, 7168
	s_nop 0
	global_load_lds_dwordx4 v201, s[46:47]
	global_load_dwordx4 v[66:69], v232, s[20:21]
	global_load_dwordx4 v[70:73], v232, s[20:21] offset:64
	global_load_dwordx4 v[74:77], v232, s[20:21] offset:128
; #define LAS __attribute__((address_space(3)))
; #define MFMA16(a, b, c) __builtin_amdgcn_mfma_f32_16x16x32_bf16((a), (b), (c), 0, 0, 0)
; #define DSEC(k) do { if (PROBE_DSEC) { const unsigned long long tn_ = __builtin_amdgcn_s_memrealtime(); if (PROBE_DSEC == (k)) tsec += tn_ - tl_; tl_ = tn_; } } while (0)
; #define XK_LOAD(R, b_, h_, hh_) do { _Pragma("unroll") for (int i = 0; i < 8; ++i) { const int p = tid + 512 * i, m = p >> 4, cb = p & 15; R[i] = *(const u32x4*)(memK + (size_t)((b_) * NMEM + m) * D + (h_) * 256 + 128 * (hh_) + 8 * cb); } } while (0)
; #define XK_WRITE(R) do { _Pragma("unroll") for (int i = 0; i < 8; ++i) { const int p = tid + 512 * i, m = p >> 4, cb = p & 15; *(LAS u32x4*)(KL + m * KSTR + 16 * cb) = R[i]; } } while (0)
; #define XV_LOAD(R, b_, h_, hh_) do { _Pragma("unroll") for (int i = 0; i < 8; ++i) { const int p = tid + 512 * i, dhr = p >> 5, c = p & 31; R[i] = *(const u32x4*)(memVT + (size_t)((h_) * 256 + 128 * (hh_) + dhr) * MROWS + (b_) * NMEM + 8 * c); } } while (0)
; #define XV_WRITE(R) do { _Pragma("unroll") for (int i = 0; i < 8; ++i) { const int p = tid + 512 * i, dhr = p >> 5, c = p & 31; u32x2 lo, hi; lo.x = R[i].x; lo.y = R[i].y; hi.x = R[i].z; hi.y = R[i].w; \
;         *(LAS u32x2*)(VL + vt_off(dhr, 2 * c)) = lo; *(LAS u32x2*)(VL + vt_off(dhr, 2 * c + 1)) = hi; } } while (0)
; DI void xattn_phase(LAS unsigned char* L, const bf16* Qx, const bf16* memK, const bf16* memVT, bf16* Ox, int G, int bid, int tid, unsigned long long& tsec) {
;     ...
;         for (int hh = 0; hh < 2; ++hh) {
;             __syncthreads();
;             XK_WRITE(ra);
;             if (hh == 0) { XV_WRITE(rb); XK_LOAD(ra, b, h, 1); XV_LOAD(rb, b, h, 1); }
;             else XK_LOAD(ra, bn, hn, 0);
;             __syncthreads();
;             DSEC(11);
; #pragma unroll
;             for (int k4 = 0; k4 < 4; ++k4) { const bf16x8 qk = *(const bf16x8*)(Qx + tq * D + h * 256 + 128 * hh + 32 * k4 + 8 * fq);
; #pragma unroll
;                 for (int k8 = 0; k8 < 4; ++k8) { bf16x8 av[4];
; #pragma unroll
;                     for (int kt = 0; kt < 4; ++kt) av[kt] = *(const LAS bf16x8*)(KL + (16 * (4 * k8 + kt) + fr) * KSTR + (32 * k4 + 8 * fq) * 2);
; #pragma unroll
;                     for (int kt = 0; kt < 4; ++kt) s[4 * k8 + kt] = MFMA16(av[kt], qk, s[4 * k8 + kt]); } }
	global_load_dwordx4 v[78:81], v232, s[20:21] offset:192
	global_load_dwordx4 v[82:85], v232, s[20:21] offset:256
	global_load_dwordx4 v[86:89], v232, s[20:21] offset:320
	global_load_dwordx4 v[90:93], v232, s[20:21] offset:384
	global_load_dwordx4 v[94:97], v232, s[20:21] offset:448
	s_lshl_b32 s46, s16, 1
	s_add_u32 s46, s46, 0
	v_lshl_add_u32 v237, s46, 6, v236
	v_lshrrev_b32_e32 v248, 2, v237
	v_and_b32_e32 v237, 3, v237
	v_lshlrev_b32_e32 v237, 6, v237
	v_lshl_add_u32 v237, v248, 11, v237
	global_load_dword v249, v237, s[24:25] offset:256
	s_lshl_b32 s46, s16, 1
	s_add_u32 s46, s46, 1
	v_lshl_add_u32 v237, s46, 6, v236
	v_lshrrev_b32_e32 v248, 2, v237
	v_and_b32_e32 v237, 3, v237
	v_lshlrev_b32_e32 v237, 6, v237
	v_lshl_add_u32 v237, v248, 11, v237
	global_load_dword v249, v237, s[24:25] offset:256
	s_lshl_b32 s46, s16, 2
	s_add_u32 s46, s46, 0
	v_lshl_add_u32 v237, s46, 6, v236
	v_lshrrev_b32_e32 v248, 3, v237
	v_and_b32_e32 v237, 7, v237
	v_lshlrev_b32_e32 v237, 6, v237
	v_lshl_add_u32 v237, v248, 11, v237
	global_load_dword v249, v237, s[42:43]
	s_lshl_b32 s46, s16, 2
	s_add_u32 s46, s46, 1
	v_lshl_add_u32 v237, s46, 6, v236
	v_lshrrev_b32_e32 v248, 3, v237
	v_and_b32_e32 v237, 7, v237
	v_lshlrev_b32_e32 v237, 6, v237
	v_lshl_add_u32 v237, v248, 11, v237
	global_load_dword v249, v237, s[42:43]
	s_lshl_b32 s46, s16, 2
	s_add_u32 s46, s46, 2
	v_lshl_add_u32 v237, s46, 6, v236
	v_lshrrev_b32_e32 v248, 3, v237
	v_and_b32_e32 v237, 7, v237
	v_lshlrev_b32_e32 v237, 6, v237
	v_lshl_add_u32 v237, v248, 11, v237
	global_load_dword v249, v237, s[42:43]
	s_lshl_b32 s46, s16, 2
	s_add_u32 s46, s46, 3
	v_lshl_add_u32 v237, s46, 6, v236
	v_lshrrev_b32_e32 v248, 3, v237
	v_and_b32_e32 v237, 7, v237
	v_lshlrev_b32_e32 v237, 6, v237
	v_lshl_add_u32 v237, v248, 11, v237
	global_load_dword v249, v237, s[42:43]
	s_waitcnt vmcnt(0)
	s_barrier
.Lxa_loop:
	s_add_u32 s44, s24, 256
	s_addc_u32 s45, s25, 0
	s_add_u32 s46, s44, 0x8000
	s_addc_u32 s47, s45, 0
	s_add_u32 m0, s49, 65536
	s_nop 0
	global_load_lds_dwordx4 v198, s[44:45]
	s_add_u32 m0, s49, 66560
	s_nop 0
	global_load_lds_dwordx4 v199, s[44:45]
	s_add_u32 m0, s49, 67584
	s_nop 0
	global_load_lds_dwordx4 v200, s[44:45]
	s_add_u32 m0, s49, 68608
	s_nop 0
	global_load_lds_dwordx4 v201, s[44:45]
	s_add_u32 m0, s49, 69632
	s_nop 0
	global_load_lds_dwordx4 v198, s[46:47]
	s_add_u32 m0, s49, 70656
	s_nop 0
	global_load_lds_dwordx4 v199, s[46:47]
	s_add_u32 m0, s49, 71680
	s_nop 0
	global_load_lds_dwordx4 v200, s[46:47]
	s_add_u32 m0, s49, 72704
	s_nop 0
	global_load_lds_dwordx4 v201, s[46:47]
	ds_read_b128 v[98:101], v206 offset:0
	ds_read_b128 v[102:105], v206 offset:4096
	ds_read_b128 v[106:109], v206 offset:8192
	ds_read_b128 v[110:113], v206 offset:12288
	ds_read_b128 v[114:117], v206 offset:16384
	ds_read_b128 v[118:121], v206 offset:20480
	ds_read_b128 v[122:125], v206 offset:24576
	ds_read_b128 v[126:129], v206 offset:28672
	ds_read_b128 v[130:133], v206 offset:32768
	ds_read_b128 v[134:137], v206 offset:36864
	ds_read_b128 v[138:141], v206 offset:40960
	ds_read_b128 v[142:145], v206 offset:45056
	ds_read_b128 v[146:149], v206 offset:49152
	ds_read_b128 v[150:153], v206 offset:53248
	ds_read_b128 v[154:157], v206 offset:57344
	ds_read_b128 v[158:161], v206 offset:61440
	s_waitcnt lgkmcnt(8)
	v_mfma_f32_16x16x32_bf16 v[2:5], v[98:101], v[66:69], 0
	ds_read_b128 v[98:101], v207 offset:0
	v_mfma_f32_16x16x32_bf16 v[6:9], v[102:105], v[66:69], 0
	ds_read_b128 v[102:105], v207 offset:4096
	v_mfma_f32_16x16x32_bf16 v[10:13], v[106:109], v[66:69], 0
	ds_read_b128 v[106:109], v207 offset:8192
	v_mfma_f32_16x16x32_bf16 v[14:17], v[110:113], v[66:69], 0
	ds_read_b128 v[110:113], v207 offset:12288
	v_mfma_f32_16x16x32_bf16 v[18:21], v[114:117], v[66:69], 0
	ds_read_b128 v[114:117], v207 offset:16384
	v_mfma_f32_16x16x32_bf16 v[22:25], v[118:121], v[66:69], 0
	ds_read_b128 v[118:121], v207 offset:20480
	v_mfma_f32_16x16x32_bf16 v[26:29], v[122:125], v[66:69], 0
	ds_read_b128 v[122:125], v207 offset:24576
	v_mfma_f32_16x16x32_bf16 v[30:33], v[126:129], v[66:69], 0
	ds_read_b128 v[126:129], v207 offset:28672
	s_waitcnt lgkmcnt(8)
	v_mfma_f32_16x16x32_bf16 v[34:37], v[130:133], v[66:69], 0
	ds_read_b128 v[130:133], v207 offset:32768
	v_mfma_f32_16x16x32_bf16 v[38:41], v[134:137], v[66:69], 0
	ds_read_b128 v[134:137], v207 offset:36864
	v_mfma_f32_16x16x32_bf16 v[42:45], v[138:141], v[66:69], 0
	ds_read_b128 v[138:141], v207 offset:40960
	v_mfma_f32_16x16x32_bf16 v[46:49], v[142:145], v[66:69], 0
	ds_read_b128 v[142:145], v207 offset:45056
	v_mfma_f32_16x16x32_bf16 v[50:53], v[146:149], v[66:69], 0
	ds_read_b128 v[146:149], v207 offset:49152
	v_mfma_f32_16x16x32_bf16 v[54:57], v[150:153], v[66:69], 0
	ds_read_b128 v[150:153], v207 offset:53248
	v_mfma_f32_16x16x32_bf16 v[58:61], v[154:157], v[66:69], 0
	ds_read_b128 v[154:157], v207 offset:57344
	v_mfma_f32_16x16x32_bf16 v[62:65], v[158:161], v[66:69], 0
	ds_read_b128 v[158:161], v207 offset:61440
	s_waitcnt lgkmcnt(8)
	v_mfma_f32_16x16x32_bf16 v[2:5], v[98:101], v[70:73], v[2:5]
	ds_read_b128 v[98:101], v208 offset:0
	v_mfma_f32_16x16x32_bf16 v[6:9], v[102:105], v[70:73], v[6:9]
	ds_read_b128 v[102:105], v208 offset:4096
	v_mfma_f32_16x16x32_bf16 v[10:13], v[106:109], v[70:73], v[10:13]
	ds_read_b128 v[106:109], v208 offset:8192
	v_mfma_f32_16x16x32_bf16 v[14:17], v[110:113], v[70:73], v[14:17]
	ds_read_b128 v[110:113], v208 offset:12288
	v_mfma_f32_16x16x32_bf16 v[18:21], v[114:117], v[70:73], v[18:21]
	ds_read_b128 v[114:117], v208 offset:16384
	v_mfma_f32_16x16x32_bf16 v[22:25], v[118:121], v[70:73], v[22:25]
	ds_read_b128 v[118:121], v208 offset:20480
	v_mfma_f32_16x16x32_bf16 v[26:29], v[122:125], v[70:73], v[26:29]
	ds_read_b128 v[122:125], v208 offset:24576
	v_mfma_f32_16x16x32_bf16 v[30:33], v[126:129], v[70:73], v[30:33]
	ds_read_b128 v[126:129], v208 offset:28672
	s_waitcnt lgkmcnt(8)
; #define LAS __attribute__((address_space(3)))
; #define MFMA16(a, b, c) __builtin_amdgcn_mfma_f32_16x16x32_bf16((a), (b), (c), 0, 0, 0)
; #define DSEC(k) do { if (PROBE_DSEC) { const unsigned long long tn_ = __builtin_amdgcn_s_memrealtime(); if (PROBE_DSEC == (k)) tsec += tn_ - tl_; tl_ = tn_; } } while (0)
; #define XK_LOAD(R, b_, h_, hh_) do { _Pragma("unroll") for (int i = 0; i < 8; ++i) { const int p = tid + 512 * i, m = p >> 4, cb = p & 15; R[i] = *(const u32x4*)(memK + (size_t)((b_) * NMEM + m) * D + (h_) * 256 + 128 * (hh_) + 8 * cb); } } while (0)
; #define XK_WRITE(R) do { _Pragma("unroll") for (int i = 0; i < 8; ++i) { const int p = tid + 512 * i, m = p >> 4, cb = p & 15; *(LAS u32x4*)(KL + m * KSTR + 16 * cb) = R[i]; } } while (0)
; #define XV_LOAD(R, b_, h_, hh_) do { _Pragma("unroll") for (int i = 0; i < 8; ++i) { const int p = tid + 512 * i, dhr = p >> 5, c = p & 31; R[i] = *(const u32x4*)(memVT + (size_t)((h_) * 256 + 128 * (hh_) + dhr) * MROWS + (b_) * NMEM + 8 * c); } } while (0)
; #define XV_WRITE(R) do { _Pragma("unroll") for (int i = 0; i < 8; ++i) { const int p = tid + 512 * i, dhr = p >> 5, c = p & 31; u32x2 lo, hi; lo.x = R[i].x; lo.y = R[i].y; hi.x = R[i].z; hi.y = R[i].w; \
;         *(LAS u32x2*)(VL + vt_off(dhr, 2 * c)) = lo; *(LAS u32x2*)(VL + vt_off(dhr, 2 * c + 1)) = hi; } } while (0)
; DI void xattn_phase(LAS unsigned char* L, const bf16* Qx, const bf16* memK, const bf16* memVT, bf16* Ox, int G, int bid, int tid, unsigned long long& tsec) {
;     ...
;         for (int hh = 0; hh < 2; ++hh) {
;             __syncthreads();
;             XK_WRITE(ra);
;             if (hh == 0) { XV_WRITE(rb); XK_LOAD(ra, b, h, 1); XV_LOAD(rb, b, h, 1); }
;             else XK_LOAD(ra, bn, hn, 0);
;             __syncthreads();
;             DSEC(11);
; #pragma unroll
;             for (int k4 = 0; k4 < 4; ++k4) { const bf16x8 qk = *(const bf16x8*)(Qx + tq * D + h * 256 + 128 * hh + 32 * k4 + 8 * fq);
; #pragma unroll
;                 for (int k8 = 0; k8 < 4; ++k8) { bf16x8 av[4];
; #pragma unroll
;                     for (int kt = 0; kt < 4; ++kt) av[kt] = *(const LAS bf16x8*)(KL + (16 * (4 * k8 + kt) + fr) * KSTR + (32 * k4 + 8 * fq) * 2);
; #pragma unroll
;                     for (int kt = 0; kt < 4; ++kt) s[4 * k8 + kt] = MFMA16(av[kt], qk, s[4 * k8 + kt]); } }
	v_mfma_f32_16x16x32_bf16 v[34:37], v[130:133], v[70:73], v[34:37]
	ds_read_b128 v[130:133], v208 offset:32768
	v_mfma_f32_16x16x32_bf16 v[38:41], v[134:137], v[70:73], v[38:41]
	ds_read_b128 v[134:137], v208 offset:36864
	v_mfma_f32_16x16x32_bf16 v[42:45], v[138:141], v[70:73], v[42:45]
	ds_read_b128 v[138:141], v208 offset:40960
	v_mfma_f32_16x16x32_bf16 v[46:49], v[142:145], v[70:73], v[46:49]
	ds_read_b128 v[142:145], v208 offset:45056
	v_mfma_f32_16x16x32_bf16 v[50:53], v[146:149], v[70:73], v[50:53]
	ds_read_b128 v[146:149], v208 offset:49152
	v_mfma_f32_16x16x32_bf16 v[54:57], v[150:153], v[70:73], v[54:57]
	ds_read_b128 v[150:153], v208 offset:53248
	v_mfma_f32_16x16x32_bf16 v[58:61], v[154:157], v[70:73], v[58:61]
	ds_read_b128 v[154:157], v208 offset:57344
	v_mfma_f32_16x16x32_bf16 v[62:65], v[158:161], v[70:73], v[62:65]
	ds_read_b128 v[158:161], v208 offset:61440
	s_waitcnt lgkmcnt(8)
	v_mfma_f32_16x16x32_bf16 v[2:5], v[98:101], v[74:77], v[2:5]
	ds_read_b128 v[98:101], v209 offset:0
	v_mfma_f32_16x16x32_bf16 v[6:9], v[102:105], v[74:77], v[6:9]
	ds_read_b128 v[102:105], v209 offset:4096
	v_mfma_f32_16x16x32_bf16 v[10:13], v[106:109], v[74:77], v[10:13]
	ds_read_b128 v[106:109], v209 offset:8192
	v_mfma_f32_16x16x32_bf16 v[14:17], v[110:113], v[74:77], v[14:17]
	ds_read_b128 v[110:113], v209 offset:12288
	v_mfma_f32_16x16x32_bf16 v[18:21], v[114:117], v[74:77], v[18:21]
	ds_read_b128 v[114:117], v209 offset:16384
	v_mfma_f32_16x16x32_bf16 v[22:25], v[118:121], v[74:77], v[22:25]
	ds_read_b128 v[118:121], v209 offset:20480
	v_mfma_f32_16x16x32_bf16 v[26:29], v[122:125], v[74:77], v[26:29]
	ds_read_b128 v[122:125], v209 offset:24576
	v_mfma_f32_16x16x32_bf16 v[30:33], v[126:129], v[74:77], v[30:33]
	ds_read_b128 v[126:129], v209 offset:28672
	s_waitcnt lgkmcnt(8)
	v_mfma_f32_16x16x32_bf16 v[34:37], v[130:133], v[74:77], v[34:37]
	ds_read_b128 v[130:133], v209 offset:32768
	v_mfma_f32_16x16x32_bf16 v[38:41], v[134:137], v[74:77], v[38:41]
	ds_read_b128 v[134:137], v209 offset:36864
	v_mfma_f32_16x16x32_bf16 v[42:45], v[138:141], v[74:77], v[42:45]
	ds_read_b128 v[138:141], v209 offset:40960
	v_mfma_f32_16x16x32_bf16 v[46:49], v[142:145], v[74:77], v[46:49]
	ds_read_b128 v[142:145], v209 offset:45056
	v_mfma_f32_16x16x32_bf16 v[50:53], v[146:149], v[74:77], v[50:53]
	ds_read_b128 v[146:149], v209 offset:49152
	v_mfma_f32_16x16x32_bf16 v[54:57], v[150:153], v[74:77], v[54:57]
	ds_read_b128 v[150:153], v209 offset:53248
	v_mfma_f32_16x16x32_bf16 v[58:61], v[154:157], v[74:77], v[58:61]
	ds_read_b128 v[154:157], v209 offset:57344
	v_mfma_f32_16x16x32_bf16 v[62:65], v[158:161], v[74:77], v[62:65]
	ds_read_b128 v[158:161], v209 offset:61440
	s_waitcnt lgkmcnt(8)
	v_mfma_f32_16x16x32_bf16 v[2:5], v[98:101], v[78:81], v[2:5]
	v_mfma_f32_16x16x32_bf16 v[6:9], v[102:105], v[78:81], v[6:9]
	v_mfma_f32_16x16x32_bf16 v[10:13], v[106:109], v[78:81], v[10:13]
	v_mfma_f32_16x16x32_bf16 v[14:17], v[110:113], v[78:81], v[14:17]
	v_mfma_f32_16x16x32_bf16 v[18:21], v[114:117], v[78:81], v[18:21]
	v_mfma_f32_16x16x32_bf16 v[22:25], v[118:121], v[78:81], v[22:25]
	v_mfma_f32_16x16x32_bf16 v[26:29], v[122:125], v[78:81], v[26:29]
	v_mfma_f32_16x16x32_bf16 v[30:33], v[126:129], v[78:81], v[30:33]
	s_waitcnt lgkmcnt(0)
	v_mfma_f32_16x16x32_bf16 v[34:37], v[130:133], v[78:81], v[34:37]
	v_mfma_f32_16x16x32_bf16 v[38:41], v[134:137], v[78:81], v[38:41]
	v_mfma_f32_16x16x32_bf16 v[42:45], v[138:141], v[78:81], v[42:45]
	v_mfma_f32_16x16x32_bf16 v[46:49], v[142:145], v[78:81], v[46:49]
	v_mfma_f32_16x16x32_bf16 v[50:53], v[146:149], v[78:81], v[50:53]
	v_mfma_f32_16x16x32_bf16 v[54:57], v[150:153], v[78:81], v[54:57]
	v_mfma_f32_16x16x32_bf16 v[58:61], v[154:157], v[78:81], v[58:61]
	v_mfma_f32_16x16x32_bf16 v[62:65], v[158:161], v[78:81], v[62:65]
	s_waitcnt vmcnt(0)
	s_barrier
	s_add_u32 s44, s42, 0
	s_addc_u32 s45, s43, 0
	v_lshrrev_b32_e32 v237, 5, v236
	v_add_u32_e32 v237, 0, v237
	v_and_b32_e32 v248, 31, v236
	v_xor_b32_e32 v248, v248, v237
	v_lshl_add_u32 v237, s16, 4, v237
	v_lshlrev_b32_e32 v237, 11, v237
	v_lshl_add_u32 v237, v248, 4, v237
	s_add_u32 m0, s49, 0
	s_nop 0
	global_load_lds_dwordx4 v237, s[44:45]
	v_lshrrev_b32_e32 v237, 5, v236
	v_add_u32_e32 v237, 2, v237
	v_and_b32_e32 v248, 31, v236
	v_xor_b32_e32 v248, v248, v237
	v_lshl_add_u32 v237, s16, 4, v237
	v_lshlrev_b32_e32 v237, 11, v237
	v_lshl_add_u32 v237, v248, 4, v237
	s_add_u32 m0, s49, 1024
	s_nop 0
	global_load_lds_dwordx4 v237, s[44:45]
	v_lshrrev_b32_e32 v237, 5, v236
	v_add_u32_e32 v237, 4, v237
	v_and_b32_e32 v248, 31, v236
	v_xor_b32_e32 v248, v248, v237
	v_lshl_add_u32 v237, s16, 4, v237
	v_lshlrev_b32_e32 v237, 11, v237
	v_lshl_add_u32 v237, v248, 4, v237
	s_add_u32 m0, s49, 2048
	s_nop 0
	global_load_lds_dwordx4 v237, s[44:45]
	v_lshrrev_b32_e32 v237, 5, v236
	v_add_u32_e32 v237, 6, v237
	v_and_b32_e32 v248, 31, v236
	v_xor_b32_e32 v248, v248, v237
	v_lshl_add_u32 v237, s16, 4, v237
	v_lshlrev_b32_e32 v237, 11, v237
	v_lshl_add_u32 v237, v248, 4, v237
	s_add_u32 m0, s49, 3072
	s_nop 0
	global_load_lds_dwordx4 v237, s[44:45]
	v_lshrrev_b32_e32 v237, 5, v236
	v_add_u32_e32 v237, 8, v237
	v_and_b32_e32 v248, 31, v236
	v_xor_b32_e32 v248, v248, v237
	v_lshl_add_u32 v237, s16, 4, v237
	v_lshlrev_b32_e32 v237, 11, v237
	v_lshl_add_u32 v237, v248, 4, v237
	s_add_u32 m0, s49, 4096
	s_nop 0
	global_load_lds_dwordx4 v237, s[44:45]
	v_lshrrev_b32_e32 v237, 5, v236
	v_add_u32_e32 v237, 10, v237
	v_and_b32_e32 v248, 31, v236
	v_xor_b32_e32 v248, v248, v237
	v_lshl_add_u32 v237, s16, 4, v237
	v_lshlrev_b32_e32 v237, 11, v237
	v_lshl_add_u32 v237, v248, 4, v237
	s_add_u32 m0, s49, 5120
	s_nop 0
	global_load_lds_dwordx4 v237, s[44:45]
	v_lshrrev_b32_e32 v237, 5, v236
	v_add_u32_e32 v237, 12, v237
	v_and_b32_e32 v248, 31, v236
	v_xor_b32_e32 v248, v248, v237
	v_lshl_add_u32 v237, s16, 4, v237
	v_lshlrev_b32_e32 v237, 11, v237
	v_lshl_add_u32 v237, v248, 4, v237
	s_add_u32 m0, s49, 6144
	s_nop 0
	global_load_lds_dwordx4 v237, s[44:45]
	v_lshrrev_b32_e32 v237, 5, v236
	v_add_u32_e32 v237, 14, v237
	v_and_b32_e32 v248, 31, v236
	v_xor_b32_e32 v248, v248, v237
	v_lshl_add_u32 v237, s16, 4, v237
	v_lshlrev_b32_e32 v237, 11, v237
	v_lshl_add_u32 v237, v248, 4, v237
	s_add_u32 m0, s49, 7168
	s_nop 0
	global_load_lds_dwordx4 v237, s[44:45]
	ds_read_b128 v[98:101], v212 offset:0
	ds_read_b128 v[102:105], v212 offset:4096
	ds_read_b128 v[106:109], v212 offset:8192
	ds_read_b128 v[110:113], v212 offset:12288
	ds_read_b128 v[114:117], v212 offset:16384
	ds_read_b128 v[118:121], v212 offset:20480
	ds_read_b128 v[122:125], v212 offset:24576
	ds_read_b128 v[126:129], v212 offset:28672
	ds_read_b128 v[130:133], v212 offset:32768
	ds_read_b128 v[134:137], v212 offset:36864
	ds_read_b128 v[138:141], v212 offset:40960
	ds_read_b128 v[142:145], v212 offset:45056
	ds_read_b128 v[146:149], v212 offset:49152
	ds_read_b128 v[150:153], v212 offset:53248
	ds_read_b128 v[154:157], v212 offset:57344
	ds_read_b128 v[158:161], v212 offset:61440
	s_waitcnt lgkmcnt(8)
; #define LAS __attribute__((address_space(3)))
; #define MFMA16(a, b, c) __builtin_amdgcn_mfma_f32_16x16x32_bf16((a), (b), (c), 0, 0, 0)
; DI void xattn_phase(LAS unsigned char* L, const bf16* Qx, const bf16* memK, const bf16* memVT, bf16* Ox, int G, int bid, int tid, unsigned long long& tsec) {
;     ...
;             for (int k4 = 0; k4 < 4; ++k4) { const bf16x8 qk = *(const bf16x8*)(Qx + tq * D + h * 256 + 128 * hh + 32 * k4 + 8 * fq);
; #pragma unroll
;                 for (int k8 = 0; k8 < 4; ++k8) { bf16x8 av[4];
; #pragma unroll
;                     for (int kt = 0; kt < 4; ++kt) av[kt] = *(const LAS bf16x8*)(KL + (16 * (4 * k8 + kt) + fr) * KSTR + (32 * k4 + 8 * fq) * 2);
; #pragma unroll
;                     for (int kt = 0; kt < 4; ++kt) s[4 * k8 + kt] = MFMA16(av[kt], qk, s[4 * k8 + kt]); } }
	v_mfma_f32_16x16x32_bf16 v[2:5], v[98:101], v[82:85], v[2:5]
	ds_read_b128 v[98:101], v213 offset:0
	v_mfma_f32_16x16x32_bf16 v[6:9], v[102:105], v[82:85], v[6:9]
	ds_read_b128 v[102:105], v213 offset:4096
	v_mfma_f32_16x16x32_bf16 v[10:13], v[106:109], v[82:85], v[10:13]
	ds_read_b128 v[106:109], v213 offset:8192
	v_mfma_f32_16x16x32_bf16 v[14:17], v[110:113], v[82:85], v[14:17]
	ds_read_b128 v[110:113], v213 offset:12288
	v_mfma_f32_16x16x32_bf16 v[18:21], v[114:117], v[82:85], v[18:21]
	ds_read_b128 v[114:117], v213 offset:16384
	v_mfma_f32_16x16x32_bf16 v[22:25], v[118:121], v[82:85], v[22:25]
	ds_read_b128 v[118:121], v213 offset:20480
	v_mfma_f32_16x16x32_bf16 v[26:29], v[122:125], v[82:85], v[26:29]
	ds_read_b128 v[122:125], v213 offset:24576
	v_mfma_f32_16x16x32_bf16 v[30:33], v[126:129], v[82:85], v[30:33]
	ds_read_b128 v[126:129], v213 offset:28672
	s_waitcnt lgkmcnt(8)
	v_mfma_f32_16x16x32_bf16 v[34:37], v[130:133], v[82:85], v[34:37]
	ds_read_b128 v[130:133], v213 offset:32768
	v_mfma_f32_16x16x32_bf16 v[38:41], v[134:137], v[82:85], v[38:41]
	ds_read_b128 v[134:137], v213 offset:36864
	v_mfma_f32_16x16x32_bf16 v[42:45], v[138:141], v[82:85], v[42:45]
	ds_read_b128 v[138:141], v213 offset:40960
	v_mfma_f32_16x16x32_bf16 v[46:49], v[142:145], v[82:85], v[46:49]
	ds_read_b128 v[142:145], v213 offset:45056
	v_mfma_f32_16x16x32_bf16 v[50:53], v[146:149], v[82:85], v[50:53]
	ds_read_b128 v[146:149], v213 offset:49152
	v_mfma_f32_16x16x32_bf16 v[54:57], v[150:153], v[82:85], v[54:57]
	ds_read_b128 v[150:153], v213 offset:53248
	v_mfma_f32_16x16x32_bf16 v[58:61], v[154:157], v[82:85], v[58:61]
	ds_read_b128 v[154:157], v213 offset:57344
	v_mfma_f32_16x16x32_bf16 v[62:65], v[158:161], v[82:85], v[62:65]
	ds_read_b128 v[158:161], v213 offset:61440
	s_waitcnt lgkmcnt(8)
	v_mfma_f32_16x16x32_bf16 v[2:5], v[98:101], v[86:89], v[2:5]
	ds_read_b128 v[98:101], v214 offset:0
	v_mfma_f32_16x16x32_bf16 v[6:9], v[102:105], v[86:89], v[6:9]
	ds_read_b128 v[102:105], v214 offset:4096
	v_mfma_f32_16x16x32_bf16 v[10:13], v[106:109], v[86:89], v[10:13]
	ds_read_b128 v[106:109], v214 offset:8192
	v_mfma_f32_16x16x32_bf16 v[14:17], v[110:113], v[86:89], v[14:17]
	ds_read_b128 v[110:113], v214 offset:12288
	v_mfma_f32_16x16x32_bf16 v[18:21], v[114:117], v[86:89], v[18:21]
	ds_read_b128 v[114:117], v214 offset:16384
	v_mfma_f32_16x16x32_bf16 v[22:25], v[118:121], v[86:89], v[22:25]
	ds_read_b128 v[118:121], v214 offset:20480
	v_mfma_f32_16x16x32_bf16 v[26:29], v[122:125], v[86:89], v[26:29]
	ds_read_b128 v[122:125], v214 offset:24576
	v_mfma_f32_16x16x32_bf16 v[30:33], v[126:129], v[86:89], v[30:33]
	ds_read_b128 v[126:129], v214 offset:28672
	s_waitcnt lgkmcnt(8)
	v_mfma_f32_16x16x32_bf16 v[34:37], v[130:133], v[86:89], v[34:37]
	ds_read_b128 v[130:133], v214 offset:32768
	v_mfma_f32_16x16x32_bf16 v[38:41], v[134:137], v[86:89], v[38:41]
	ds_read_b128 v[134:137], v214 offset:36864
	v_mfma_f32_16x16x32_bf16 v[42:45], v[138:141], v[86:89], v[42:45]
	ds_read_b128 v[138:141], v214 offset:40960
	v_mfma_f32_16x16x32_bf16 v[46:49], v[142:145], v[86:89], v[46:49]
	ds_read_b128 v[142:145], v214 offset:45056
	v_mfma_f32_16x16x32_bf16 v[50:53], v[146:149], v[86:89], v[50:53]
	ds_read_b128 v[146:149], v214 offset:49152
	v_mfma_f32_16x16x32_bf16 v[54:57], v[150:153], v[86:89], v[54:57]
	ds_read_b128 v[150:153], v214 offset:53248
	v_mfma_f32_16x16x32_bf16 v[58:61], v[154:157], v[86:89], v[58:61]
	ds_read_b128 v[154:157], v214 offset:57344
	v_mfma_f32_16x16x32_bf16 v[62:65], v[158:161], v[86:89], v[62:65]
	ds_read_b128 v[158:161], v214 offset:61440
	s_waitcnt lgkmcnt(8)
	v_mfma_f32_16x16x32_bf16 v[2:5], v[98:101], v[90:93], v[2:5]
	ds_read_b128 v[98:101], v215 offset:0
	v_mfma_f32_16x16x32_bf16 v[6:9], v[102:105], v[90:93], v[6:9]
	ds_read_b128 v[102:105], v215 offset:4096
	v_mfma_f32_16x16x32_bf16 v[10:13], v[106:109], v[90:93], v[10:13]
	ds_read_b128 v[106:109], v215 offset:8192
	v_mfma_f32_16x16x32_bf16 v[14:17], v[110:113], v[90:93], v[14:17]
	ds_read_b128 v[110:113], v215 offset:12288
	v_mfma_f32_16x16x32_bf16 v[18:21], v[114:117], v[90:93], v[18:21]
	ds_read_b128 v[114:117], v215 offset:16384
	v_mfma_f32_16x16x32_bf16 v[22:25], v[118:121], v[90:93], v[22:25]
	ds_read_b128 v[118:121], v215 offset:20480
	v_mfma_f32_16x16x32_bf16 v[26:29], v[122:125], v[90:93], v[26:29]
	ds_read_b128 v[122:125], v215 offset:24576
	v_mfma_f32_16x16x32_bf16 v[30:33], v[126:129], v[90:93], v[30:33]
	ds_read_b128 v[126:129], v215 offset:28672
	s_waitcnt lgkmcnt(8)
	v_mfma_f32_16x16x32_bf16 v[34:37], v[130:133], v[90:93], v[34:37]
	ds_read_b128 v[130:133], v215 offset:32768
	v_mfma_f32_16x16x32_bf16 v[38:41], v[134:137], v[90:93], v[38:41]
	ds_read_b128 v[134:137], v215 offset:36864
	v_mfma_f32_16x16x32_bf16 v[42:45], v[138:141], v[90:93], v[42:45]
	ds_read_b128 v[138:141], v215 offset:40960
	v_mfma_f32_16x16x32_bf16 v[46:49], v[142:145], v[90:93], v[46:49]
	ds_read_b128 v[142:145], v215 offset:45056
	v_mfma_f32_16x16x32_bf16 v[50:53], v[146:149], v[90:93], v[50:53]
	ds_read_b128 v[146:149], v215 offset:49152
	v_mfma_f32_16x16x32_bf16 v[54:57], v[150:153], v[90:93], v[54:57]
	ds_read_b128 v[150:153], v215 offset:53248
	v_mfma_f32_16x16x32_bf16 v[58:61], v[154:157], v[90:93], v[58:61]
	ds_read_b128 v[154:157], v215 offset:57344
	v_mfma_f32_16x16x32_bf16 v[62:65], v[158:161], v[90:93], v[62:65]
	ds_read_b128 v[158:161], v215 offset:61440
	s_waitcnt lgkmcnt(8)
; #define LAS __attribute__((address_space(3)))
; #define MFMA16(a, b, c) __builtin_amdgcn_mfma_f32_16x16x32_bf16((a), (b), (c), 0, 0, 0)
; #define DSEC(k) do { if (PROBE_DSEC) { const unsigned long long tn_ = __builtin_amdgcn_s_memrealtime(); if (PROBE_DSEC == (k)) tsec += tn_ - tl_; tl_ = tn_; } } while (0)
; DI void xattn_phase(LAS unsigned char* L, const bf16* Qx, const bf16* memK, const bf16* memVT, bf16* Ox, int G, int bid, int tid, unsigned long long& tsec) {
;     ...
;             for (int k4 = 0; k4 < 4; ++k4) { const bf16x8 qk = *(const bf16x8*)(Qx + tq * D + h * 256 + 128 * hh + 32 * k4 + 8 * fq);
; #pragma unroll
;                 for (int k8 = 0; k8 < 4; ++k8) { bf16x8 av[4];
; #pragma unroll
;                     for (int kt = 0; kt < 4; ++kt) av[kt] = *(const LAS bf16x8*)(KL + (16 * (4 * k8 + kt) + fr) * KSTR + (32 * k4 + 8 * fq) * 2);
; #pragma unroll
;                     for (int kt = 0; kt < 4; ++kt) s[4 * k8 + kt] = MFMA16(av[kt], qk, s[4 * k8 + kt]); } }
;         }
;         DSEC(12);
;         float mx = -INFINITY;
; #pragma unroll
;         for (int kt = 0; kt < 16; ++kt)
; #pragma unroll
;             for (int e = 0; e < 4; ++e) { const float v = s[kt][e] * 0.0625f; s[kt][e] = v; mx = fmaxf(mx, v); }
;         mx = fmaxf(mx, __shfl_xor(mx, 16)); mx = fmaxf(mx, __shfl_xor(mx, 32));
	v_mfma_f32_16x16x32_bf16 v[2:5], v[98:101], v[94:97], v[2:5]
	v_mfma_f32_16x16x32_bf16 v[6:9], v[102:105], v[94:97], v[6:9]
	v_mfma_f32_16x16x32_bf16 v[10:13], v[106:109], v[94:97], v[10:13]
	v_mfma_f32_16x16x32_bf16 v[14:17], v[110:113], v[94:97], v[14:17]
	v_mfma_f32_16x16x32_bf16 v[18:21], v[114:117], v[94:97], v[18:21]
	v_mfma_f32_16x16x32_bf16 v[22:25], v[118:121], v[94:97], v[22:25]
	v_mfma_f32_16x16x32_bf16 v[26:29], v[122:125], v[94:97], v[26:29]
	v_mfma_f32_16x16x32_bf16 v[30:33], v[126:129], v[94:97], v[30:33]
	s_waitcnt lgkmcnt(0)
	v_mfma_f32_16x16x32_bf16 v[34:37], v[130:133], v[94:97], v[34:37]
	v_mfma_f32_16x16x32_bf16 v[38:41], v[134:137], v[94:97], v[38:41]
	v_mfma_f32_16x16x32_bf16 v[42:45], v[138:141], v[94:97], v[42:45]
	v_mfma_f32_16x16x32_bf16 v[46:49], v[142:145], v[94:97], v[46:49]
	v_mfma_f32_16x16x32_bf16 v[50:53], v[146:149], v[94:97], v[50:53]
	v_mfma_f32_16x16x32_bf16 v[54:57], v[150:153], v[94:97], v[54:57]
	v_mfma_f32_16x16x32_bf16 v[58:61], v[154:157], v[94:97], v[58:61]
	v_mfma_f32_16x16x32_bf16 v[62:65], v[158:161], v[94:97], v[62:65]
	v_mul_f32_e32 v237, 0x3d800000, v2
	v_mul_f32_e32 v248, 0x3d800000, v3
	v_max_f32_e32 v249, v237, v248
	v_mul_f32_e32 v237, 0x3d800000, v4
	v_mul_f32_e32 v248, 0x3d800000, v5
	v_max3_f32 v249, v249, v237, v248
	v_mul_f32_e32 v237, 0x3d800000, v6
	v_mul_f32_e32 v248, 0x3d800000, v7
	v_max3_f32 v249, v249, v237, v248
	v_mul_f32_e32 v237, 0x3d800000, v8
	v_mul_f32_e32 v248, 0x3d800000, v9
	v_max3_f32 v249, v249, v237, v248
	v_mul_f32_e32 v237, 0x3d800000, v10
	v_mul_f32_e32 v248, 0x3d800000, v11
	v_max3_f32 v249, v249, v237, v248
	v_mul_f32_e32 v237, 0x3d800000, v12
	v_mul_f32_e32 v248, 0x3d800000, v13
	v_max3_f32 v249, v249, v237, v248
	v_mul_f32_e32 v237, 0x3d800000, v14
	v_mul_f32_e32 v248, 0x3d800000, v15
	v_max3_f32 v249, v249, v237, v248
	v_mul_f32_e32 v237, 0x3d800000, v16
	v_mul_f32_e32 v248, 0x3d800000, v17
	v_max3_f32 v249, v249, v237, v248
	v_mul_f32_e32 v237, 0x3d800000, v18
	v_mul_f32_e32 v248, 0x3d800000, v19
	v_max3_f32 v249, v249, v237, v248
	v_mul_f32_e32 v237, 0x3d800000, v20
	v_mul_f32_e32 v248, 0x3d800000, v21
	v_max3_f32 v249, v249, v237, v248
	v_mul_f32_e32 v237, 0x3d800000, v22
	v_mul_f32_e32 v248, 0x3d800000, v23
	v_max3_f32 v249, v249, v237, v248
	v_mul_f32_e32 v237, 0x3d800000, v24
	v_mul_f32_e32 v248, 0x3d800000, v25
	v_max3_f32 v249, v249, v237, v248
	v_mul_f32_e32 v237, 0x3d800000, v26
	v_mul_f32_e32 v248, 0x3d800000, v27
	v_max3_f32 v249, v249, v237, v248
	v_mul_f32_e32 v237, 0x3d800000, v28
	v_mul_f32_e32 v248, 0x3d800000, v29
	v_max3_f32 v249, v249, v237, v248
	v_mul_f32_e32 v237, 0x3d800000, v30
	v_mul_f32_e32 v248, 0x3d800000, v31
	v_max3_f32 v249, v249, v237, v248
	v_mul_f32_e32 v237, 0x3d800000, v32
	v_mul_f32_e32 v248, 0x3d800000, v33
	v_max3_f32 v249, v249, v237, v248
	v_mul_f32_e32 v237, 0x3d800000, v34
	v_mul_f32_e32 v248, 0x3d800000, v35
	v_max3_f32 v249, v249, v237, v248
	v_mul_f32_e32 v237, 0x3d800000, v36
	v_mul_f32_e32 v248, 0x3d800000, v37
	v_max3_f32 v249, v249, v237, v248
	v_mul_f32_e32 v237, 0x3d800000, v38
	v_mul_f32_e32 v248, 0x3d800000, v39
	v_max3_f32 v249, v249, v237, v248
	v_mul_f32_e32 v237, 0x3d800000, v40
	v_mul_f32_e32 v248, 0x3d800000, v41
	v_max3_f32 v249, v249, v237, v248
	v_mul_f32_e32 v237, 0x3d800000, v42
	v_mul_f32_e32 v248, 0x3d800000, v43
	v_max3_f32 v249, v249, v237, v248
	v_mul_f32_e32 v237, 0x3d800000, v44
	v_mul_f32_e32 v248, 0x3d800000, v45
	v_max3_f32 v249, v249, v237, v248
	v_mul_f32_e32 v237, 0x3d800000, v46
	v_mul_f32_e32 v248, 0x3d800000, v47
	v_max3_f32 v249, v249, v237, v248
	v_mul_f32_e32 v237, 0x3d800000, v48
	v_mul_f32_e32 v248, 0x3d800000, v49
	v_max3_f32 v249, v249, v237, v248
	v_mul_f32_e32 v237, 0x3d800000, v50
	v_mul_f32_e32 v248, 0x3d800000, v51
	v_max3_f32 v249, v249, v237, v248
	v_mul_f32_e32 v237, 0x3d800000, v52
	v_mul_f32_e32 v248, 0x3d800000, v53
	v_max3_f32 v249, v249, v237, v248
	v_mul_f32_e32 v237, 0x3d800000, v54
	v_mul_f32_e32 v248, 0x3d800000, v55
	v_max3_f32 v249, v249, v237, v248
	v_mul_f32_e32 v237, 0x3d800000, v56
	v_mul_f32_e32 v248, 0x3d800000, v57
	v_max3_f32 v249, v249, v237, v248
	v_mul_f32_e32 v237, 0x3d800000, v58
	v_mul_f32_e32 v248, 0x3d800000, v59
	v_max3_f32 v249, v249, v237, v248
	v_mul_f32_e32 v237, 0x3d800000, v60
	v_mul_f32_e32 v248, 0x3d800000, v61
	v_max3_f32 v249, v249, v237, v248
	v_mul_f32_e32 v237, 0x3d800000, v62
	v_mul_f32_e32 v248, 0x3d800000, v63
	v_max3_f32 v249, v249, v237, v248
	v_mul_f32_e32 v237, 0x3d800000, v64
	v_mul_f32_e32 v248, 0x3d800000, v65
	v_max3_f32 v249, v249, v237, v248
	ds_bpermute_b32 v237, v234, v249
	s_waitcnt lgkmcnt(0)
	v_max_f32_e32 v237, v237, v237
	v_max_f32_e32 v249, v249, v237
	ds_bpermute_b32 v237, v235, v249
	s_waitcnt lgkmcnt(0)
; DI void xattn_phase(LAS unsigned char* L, const bf16* Qx, const bf16* memK, const bf16* memVT, bf16* Ox, int G, int bid, int tid, unsigned long long& tsec) {
;     ...
;             for (int e = 0; e < 4; ++e) { const float v = s[kt][e] * 0.0625f; s[kt][e] = v; mx = fmaxf(mx, v); }
;         mx = fmaxf(mx, __shfl_xor(mx, 16)); mx = fmaxf(mx, __shfl_xor(mx, 32));
;         float den = 0.f;
; #pragma unroll
;         for (int kt = 0; kt < 16; ++kt)
; #pragma unroll
;             for (int e = 0; e < 4; ++e) { const float p = __expf(s[kt][e] - mx); s[kt][e] = p; den += p; }
	v_max_f32_e32 v237, v237, v237
	v_max_f32_e32 v249, v249, v237
	v_fma_f32 v2, v2, s48, -v249
	v_fma_f32 v3, v3, s48, -v249
	v_fma_f32 v4, v4, s48, -v249
	v_fma_f32 v5, v5, s48, -v249
	v_fma_f32 v6, v6, s48, -v249
	v_fma_f32 v7, v7, s48, -v249
	v_fma_f32 v8, v8, s48, -v249
	v_fma_f32 v9, v9, s48, -v249
	v_fma_f32 v10, v10, s48, -v249
	v_fma_f32 v11, v11, s48, -v249
	v_fma_f32 v12, v12, s48, -v249
	v_fma_f32 v13, v13, s48, -v249
	v_fma_f32 v14, v14, s48, -v249
	v_fma_f32 v15, v15, s48, -v249
	v_fma_f32 v16, v16, s48, -v249
	v_fma_f32 v17, v17, s48, -v249
	v_fma_f32 v18, v18, s48, -v249
	v_fma_f32 v19, v19, s48, -v249
	v_fma_f32 v20, v20, s48, -v249
	v_fma_f32 v21, v21, s48, -v249
	v_fma_f32 v22, v22, s48, -v249
	v_fma_f32 v23, v23, s48, -v249
	v_fma_f32 v24, v24, s48, -v249
	v_fma_f32 v25, v25, s48, -v249
	v_fma_f32 v26, v26, s48, -v249
	v_fma_f32 v27, v27, s48, -v249
	v_fma_f32 v28, v28, s48, -v249
	v_fma_f32 v29, v29, s48, -v249
	v_fma_f32 v30, v30, s48, -v249
	v_fma_f32 v31, v31, s48, -v249
	v_fma_f32 v32, v32, s48, -v249
	v_fma_f32 v33, v33, s48, -v249
	v_fma_f32 v34, v34, s48, -v249
	v_fma_f32 v35, v35, s48, -v249
	v_fma_f32 v36, v36, s48, -v249
	v_fma_f32 v37, v37, s48, -v249
	v_fma_f32 v38, v38, s48, -v249
	v_fma_f32 v39, v39, s48, -v249
	v_fma_f32 v40, v40, s48, -v249
	v_fma_f32 v41, v41, s48, -v249
	v_fma_f32 v42, v42, s48, -v249
	v_fma_f32 v43, v43, s48, -v249
	v_fma_f32 v44, v44, s48, -v249
	v_fma_f32 v45, v45, s48, -v249
	v_fma_f32 v46, v46, s48, -v249
	v_fma_f32 v47, v47, s48, -v249
	v_fma_f32 v48, v48, s48, -v249
	v_fma_f32 v49, v49, s48, -v249
	v_fma_f32 v50, v50, s48, -v249
	v_fma_f32 v51, v51, s48, -v249
	v_fma_f32 v52, v52, s48, -v249
	v_fma_f32 v53, v53, s48, -v249
	v_fma_f32 v54, v54, s48, -v249
	v_fma_f32 v55, v55, s48, -v249
	v_fma_f32 v56, v56, s48, -v249
	v_fma_f32 v57, v57, s48, -v249
	v_fma_f32 v58, v58, s48, -v249
	v_fma_f32 v59, v59, s48, -v249
	v_fma_f32 v60, v60, s48, -v249
	v_fma_f32 v61, v61, s48, -v249
	v_fma_f32 v62, v62, s48, -v249
	v_fma_f32 v63, v63, s48, -v249
	v_fma_f32 v64, v64, s48, -v249
	v_fma_f32 v65, v65, s48, -v249
	v_mul_f32_e32 v2, 0x3fb8aa3b, v2
	v_mul_f32_e32 v3, 0x3fb8aa3b, v3
	v_mul_f32_e32 v4, 0x3fb8aa3b, v4
	v_mul_f32_e32 v5, 0x3fb8aa3b, v5
	v_mul_f32_e32 v6, 0x3fb8aa3b, v6
	v_mul_f32_e32 v7, 0x3fb8aa3b, v7
	v_mul_f32_e32 v8, 0x3fb8aa3b, v8
	v_mul_f32_e32 v9, 0x3fb8aa3b, v9
	v_mul_f32_e32 v10, 0x3fb8aa3b, v10
	v_mul_f32_e32 v11, 0x3fb8aa3b, v11
	v_mul_f32_e32 v12, 0x3fb8aa3b, v12
	v_mul_f32_e32 v13, 0x3fb8aa3b, v13
	v_mul_f32_e32 v14, 0x3fb8aa3b, v14
	v_mul_f32_e32 v15, 0x3fb8aa3b, v15
	v_mul_f32_e32 v16, 0x3fb8aa3b, v16
	v_mul_f32_e32 v17, 0x3fb8aa3b, v17
	v_mul_f32_e32 v18, 0x3fb8aa3b, v18
	v_mul_f32_e32 v19, 0x3fb8aa3b, v19
	v_mul_f32_e32 v20, 0x3fb8aa3b, v20
	v_mul_f32_e32 v21, 0x3fb8aa3b, v21
	v_mul_f32_e32 v22, 0x3fb8aa3b, v22
	v_mul_f32_e32 v23, 0x3fb8aa3b, v23
	v_mul_f32_e32 v24, 0x3fb8aa3b, v24
	v_mul_f32_e32 v25, 0x3fb8aa3b, v25
	v_mul_f32_e32 v26, 0x3fb8aa3b, v26
	v_mul_f32_e32 v27, 0x3fb8aa3b, v27
	v_mul_f32_e32 v28, 0x3fb8aa3b, v28
	v_mul_f32_e32 v29, 0x3fb8aa3b, v29
	v_mul_f32_e32 v30, 0x3fb8aa3b, v30
	v_mul_f32_e32 v31, 0x3fb8aa3b, v31
	v_mul_f32_e32 v32, 0x3fb8aa3b, v32
	v_mul_f32_e32 v33, 0x3fb8aa3b, v33
	v_mul_f32_e32 v34, 0x3fb8aa3b, v34
	v_mul_f32_e32 v35, 0x3fb8aa3b, v35
	v_mul_f32_e32 v36, 0x3fb8aa3b, v36
	v_mul_f32_e32 v37, 0x3fb8aa3b, v37
	v_mul_f32_e32 v38, 0x3fb8aa3b, v38
	v_mul_f32_e32 v39, 0x3fb8aa3b, v39
	v_mul_f32_e32 v40, 0x3fb8aa3b, v40
	v_mul_f32_e32 v41, 0x3fb8aa3b, v41
	v_mul_f32_e32 v42, 0x3fb8aa3b, v42
	v_mul_f32_e32 v43, 0x3fb8aa3b, v43
	v_mul_f32_e32 v44, 0x3fb8aa3b, v44
	v_mul_f32_e32 v45, 0x3fb8aa3b, v45
	v_mul_f32_e32 v46, 0x3fb8aa3b, v46
	v_mul_f32_e32 v47, 0x3fb8aa3b, v47
	v_mul_f32_e32 v48, 0x3fb8aa3b, v48
	v_mul_f32_e32 v49, 0x3fb8aa3b, v49
	v_mul_f32_e32 v50, 0x3fb8aa3b, v50
	v_mul_f32_e32 v51, 0x3fb8aa3b, v51
	v_mul_f32_e32 v52, 0x3fb8aa3b, v52
	v_mul_f32_e32 v53, 0x3fb8aa3b, v53
	v_mul_f32_e32 v54, 0x3fb8aa3b, v54
	v_mul_f32_e32 v55, 0x3fb8aa3b, v55
	v_mul_f32_e32 v56, 0x3fb8aa3b, v56
	v_mul_f32_e32 v57, 0x3fb8aa3b, v57
	v_mul_f32_e32 v58, 0x3fb8aa3b, v58
	v_mul_f32_e32 v59, 0x3fb8aa3b, v59
	v_mul_f32_e32 v60, 0x3fb8aa3b, v60
	v_mul_f32_e32 v61, 0x3fb8aa3b, v61
	v_mul_f32_e32 v62, 0x3fb8aa3b, v62
	v_mul_f32_e32 v63, 0x3fb8aa3b, v63
	v_mul_f32_e32 v64, 0x3fb8aa3b, v64
	v_mul_f32_e32 v65, 0x3fb8aa3b, v65
	v_exp_f32_e32 v2, v2
	v_exp_f32_e32 v3, v3
	v_exp_f32_e32 v4, v4
	v_exp_f32_e32 v5, v5
	v_exp_f32_e32 v6, v6
	v_exp_f32_e32 v7, v7
	v_exp_f32_e32 v8, v8
	v_exp_f32_e32 v9, v9
	v_exp_f32_e32 v10, v10
	v_exp_f32_e32 v11, v11
	v_exp_f32_e32 v12, v12
	v_exp_f32_e32 v13, v13
	v_exp_f32_e32 v14, v14
	v_exp_f32_e32 v15, v15
	v_exp_f32_e32 v16, v16
	v_exp_f32_e32 v17, v17
	v_exp_f32_e32 v18, v18
	v_exp_f32_e32 v19, v19
	v_exp_f32_e32 v20, v20
	v_exp_f32_e32 v21, v21
	v_exp_f32_e32 v22, v22
	v_exp_f32_e32 v23, v23
	v_exp_f32_e32 v24, v24
	v_exp_f32_e32 v25, v25
	v_exp_f32_e32 v26, v26
	v_exp_f32_e32 v27, v27
	v_exp_f32_e32 v28, v28
	v_exp_f32_e32 v29, v29
	v_exp_f32_e32 v30, v30
	v_exp_f32_e32 v31, v31
	v_exp_f32_e32 v32, v32
	v_exp_f32_e32 v33, v33
	v_exp_f32_e32 v34, v34
	v_exp_f32_e32 v35, v35
	v_exp_f32_e32 v36, v36
	v_exp_f32_e32 v37, v37
	v_exp_f32_e32 v38, v38
	v_exp_f32_e32 v39, v39
	v_exp_f32_e32 v40, v40
	v_exp_f32_e32 v41, v41
	v_exp_f32_e32 v42, v42
	v_exp_f32_e32 v43, v43
	v_exp_f32_e32 v44, v44
	v_exp_f32_e32 v45, v45
	v_exp_f32_e32 v46, v46
	v_exp_f32_e32 v47, v47
	v_exp_f32_e32 v48, v48
	v_exp_f32_e32 v49, v49
	v_exp_f32_e32 v50, v50
	v_exp_f32_e32 v51, v51
	v_exp_f32_e32 v52, v52
	v_exp_f32_e32 v53, v53
	v_exp_f32_e32 v54, v54
; DI unsigned pk2(float lo, float hi) { const bf2_t r = __builtin_convertvector((f32x2_t){lo, hi}, bf2_t); return __builtin_bit_cast(unsigned, r); }
; #define DSEC(k) do { if (PROBE_DSEC) { const unsigned long long tn_ = __builtin_amdgcn_s_memrealtime(); if (PROBE_DSEC == (k)) tsec += tn_ - tl_; tl_ = tn_; } } while (0)
; #define XV_LOAD(R, b_, h_, hh_) do { _Pragma("unroll") for (int i = 0; i < 8; ++i) { const int p = tid + 512 * i, dhr = p >> 5, c = p & 31; R[i] = *(const u32x4*)(memVT + (size_t)((h_) * 256 + 128 * (hh_) + dhr) * MROWS + (b_) * NMEM + 8 * c); } } while (0)
; #define XV_WRITE(R) do { _Pragma("unroll") for (int i = 0; i < 8; ++i) { const int p = tid + 512 * i, dhr = p >> 5, c = p & 31; u32x2 lo, hi; lo.x = R[i].x; lo.y = R[i].y; hi.x = R[i].z; hi.y = R[i].w; \
;         *(LAS u32x2*)(VL + vt_off(dhr, 2 * c)) = lo; *(LAS u32x2*)(VL + vt_off(dhr, 2 * c + 1)) = hi; } } while (0)
; DI void xattn_phase(LAS unsigned char* L, const bf16* Qx, const bf16* memK, const bf16* memVT, bf16* Ox, int G, int bid, int tid, unsigned long long& tsec) {
;     ...
;         float den = 0.f;
; #pragma unroll
;         for (int kt = 0; kt < 16; ++kt)
; #pragma unroll
;             for (int e = 0; e < 4; ++e) { const float p = __expf(s[kt][e] - mx); s[kt][e] = p; den += p; }
;         den += __shfl_xor(den, 16); den += __shfl_xor(den, 32);
;         DSEC(13);
;         bf16x8 pf[8];
; #pragma unroll
;         for (int pp = 0; pp < 8; ++pp) { u32x4 pw; pw.x = pk2(s[2 * pp][0], s[2 * pp][1]); pw.y = pk2(s[2 * pp][2], s[2 * pp][3]); pw.z = pk2(s[2 * pp + 1][0], s[2 * pp + 1][1]); pw.w = pk2(s[2 * pp + 1][2], s[2 * pp + 1][3]); pf[pp] = mk8(pw); }
;         const float inv = __builtin_amdgcn_rcpf(den);
; #pragma unroll
;         for (int hh = 0; hh < 2; ++hh) {
;             if (hh == 1) { DSEC(14); __syncthreads(); XV_WRITE(rb); XV_LOAD(rb, bn, hn, 0); __syncthreads(); DSEC(15); }
	v_exp_f32_e32 v55, v55
	v_exp_f32_e32 v56, v56
	v_exp_f32_e32 v57, v57
	v_exp_f32_e32 v58, v58
	v_exp_f32_e32 v59, v59
	v_exp_f32_e32 v60, v60
	v_exp_f32_e32 v61, v61
	v_exp_f32_e32 v62, v62
	v_exp_f32_e32 v63, v63
	v_exp_f32_e32 v64, v64
	v_exp_f32_e32 v65, v65
	s_nop 0
	v_add_f32_e32 v237, v2, v3
	v_add_f32_e32 v237, v237, v4
	v_add_f32_e32 v237, v237, v5
	v_add_f32_e32 v237, v237, v6
	v_add_f32_e32 v237, v237, v7
	v_add_f32_e32 v237, v237, v8
	v_add_f32_e32 v237, v237, v9
	v_add_f32_e32 v237, v237, v10
	v_add_f32_e32 v237, v237, v11
	v_add_f32_e32 v237, v237, v12
	v_add_f32_e32 v237, v237, v13
	v_add_f32_e32 v237, v237, v14
	v_add_f32_e32 v237, v237, v15
	v_add_f32_e32 v237, v237, v16
	v_add_f32_e32 v237, v237, v17
	v_add_f32_e32 v237, v237, v18
	v_add_f32_e32 v237, v237, v19
	v_add_f32_e32 v237, v237, v20
	v_add_f32_e32 v237, v237, v21
	v_add_f32_e32 v237, v237, v22
	v_add_f32_e32 v237, v237, v23
	v_add_f32_e32 v237, v237, v24
	v_add_f32_e32 v237, v237, v25
	v_add_f32_e32 v237, v237, v26
	v_add_f32_e32 v237, v237, v27
	v_add_f32_e32 v237, v237, v28
	v_add_f32_e32 v237, v237, v29
	v_add_f32_e32 v237, v237, v30
	v_add_f32_e32 v237, v237, v31
	v_add_f32_e32 v237, v237, v32
	v_add_f32_e32 v237, v237, v33
	v_add_f32_e32 v237, v237, v34
	v_add_f32_e32 v237, v237, v35
	v_add_f32_e32 v237, v237, v36
	v_add_f32_e32 v237, v237, v37
	v_add_f32_e32 v237, v237, v38
	v_add_f32_e32 v237, v237, v39
	v_add_f32_e32 v237, v237, v40
	v_add_f32_e32 v237, v237, v41
	v_add_f32_e32 v237, v237, v42
	v_add_f32_e32 v237, v237, v43
	v_add_f32_e32 v237, v237, v44
	v_add_f32_e32 v237, v237, v45
	v_add_f32_e32 v237, v237, v46
	v_add_f32_e32 v237, v237, v47
	v_add_f32_e32 v237, v237, v48
	v_add_f32_e32 v237, v237, v49
	v_add_f32_e32 v237, v237, v50
	v_add_f32_e32 v237, v237, v51
	v_add_f32_e32 v237, v237, v52
	v_add_f32_e32 v237, v237, v53
	v_add_f32_e32 v237, v237, v54
	v_add_f32_e32 v237, v237, v55
	v_add_f32_e32 v237, v237, v56
	v_add_f32_e32 v237, v237, v57
	v_add_f32_e32 v237, v237, v58
	v_add_f32_e32 v237, v237, v59
	v_add_f32_e32 v237, v237, v60
	v_add_f32_e32 v237, v237, v61
	v_add_f32_e32 v237, v237, v62
	v_add_f32_e32 v237, v237, v63
	v_add_f32_e32 v237, v237, v64
	v_add_f32_e32 v237, v237, v65
	ds_bpermute_b32 v248, v234, v237
	s_waitcnt lgkmcnt(0)
	v_add_f32_e32 v237, v237, v248
	ds_bpermute_b32 v248, v235, v237
	s_waitcnt lgkmcnt(0)
	v_add_f32_e32 v237, v237, v248
	v_rcp_f32_e32 v0, v237
	v_cvt_pk_bf16_f32 v162, v2, v3
	v_cvt_pk_bf16_f32 v163, v4, v5
	v_cvt_pk_bf16_f32 v164, v6, v7
	v_cvt_pk_bf16_f32 v165, v8, v9
	v_cvt_pk_bf16_f32 v166, v10, v11
	v_cvt_pk_bf16_f32 v167, v12, v13
	v_cvt_pk_bf16_f32 v168, v14, v15
	v_cvt_pk_bf16_f32 v169, v16, v17
	v_cvt_pk_bf16_f32 v170, v18, v19
	v_cvt_pk_bf16_f32 v171, v20, v21
	v_cvt_pk_bf16_f32 v172, v22, v23
	v_cvt_pk_bf16_f32 v173, v24, v25
	v_cvt_pk_bf16_f32 v174, v26, v27
	v_cvt_pk_bf16_f32 v175, v28, v29
	v_cvt_pk_bf16_f32 v176, v30, v31
	v_cvt_pk_bf16_f32 v177, v32, v33
	v_cvt_pk_bf16_f32 v178, v34, v35
	v_cvt_pk_bf16_f32 v179, v36, v37
	v_cvt_pk_bf16_f32 v180, v38, v39
	v_cvt_pk_bf16_f32 v181, v40, v41
	v_cvt_pk_bf16_f32 v182, v42, v43
	v_cvt_pk_bf16_f32 v183, v44, v45
	v_cvt_pk_bf16_f32 v184, v46, v47
	v_cvt_pk_bf16_f32 v185, v48, v49
	v_cvt_pk_bf16_f32 v186, v50, v51
	v_cvt_pk_bf16_f32 v187, v52, v53
	v_cvt_pk_bf16_f32 v188, v54, v55
	v_cvt_pk_bf16_f32 v189, v56, v57
	v_cvt_pk_bf16_f32 v190, v58, v59
	v_cvt_pk_bf16_f32 v191, v60, v61
	v_cvt_pk_bf16_f32 v192, v62, v63
	v_cvt_pk_bf16_f32 v193, v64, v65
	s_waitcnt vmcnt(0)
	s_barrier
	s_add_u32 s44, s42, 262144
	s_addc_u32 s45, s43, 0
	v_lshrrev_b32_e32 v237, 5, v236
	v_add_u32_e32 v237, 0, v237
	v_and_b32_e32 v248, 31, v236
	v_xor_b32_e32 v248, v248, v237
	v_lshl_add_u32 v237, s16, 4, v237
	v_lshlrev_b32_e32 v237, 11, v237
	v_lshl_add_u32 v237, v248, 4, v237
	s_add_u32 m0, s49, 65536
	s_nop 0
	global_load_lds_dwordx4 v237, s[44:45]
	v_lshrrev_b32_e32 v237, 5, v236
	v_add_u32_e32 v237, 2, v237
	v_and_b32_e32 v248, 31, v236
	v_xor_b32_e32 v248, v248, v237
	v_lshl_add_u32 v237, s16, 4, v237
	v_lshlrev_b32_e32 v237, 11, v237
	v_lshl_add_u32 v237, v248, 4, v237
	s_add_u32 m0, s49, 66560
	s_nop 0
	global_load_lds_dwordx4 v237, s[44:45]
	v_lshrrev_b32_e32 v237, 5, v236
	v_add_u32_e32 v237, 4, v237
	v_and_b32_e32 v248, 31, v236
	v_xor_b32_e32 v248, v248, v237
	v_lshl_add_u32 v237, s16, 4, v237
	v_lshlrev_b32_e32 v237, 11, v237
	v_lshl_add_u32 v237, v248, 4, v237
	s_add_u32 m0, s49, 67584
	s_nop 0
	global_load_lds_dwordx4 v237, s[44:45]
	v_lshrrev_b32_e32 v237, 5, v236
	v_add_u32_e32 v237, 6, v237
	v_and_b32_e32 v248, 31, v236
	v_xor_b32_e32 v248, v248, v237
	v_lshl_add_u32 v237, s16, 4, v237
	v_lshlrev_b32_e32 v237, 11, v237
	v_lshl_add_u32 v237, v248, 4, v237
	s_add_u32 m0, s49, 68608
	s_nop 0
	global_load_lds_dwordx4 v237, s[44:45]
	v_lshrrev_b32_e32 v237, 5, v236
	v_add_u32_e32 v237, 8, v237
	v_and_b32_e32 v248, 31, v236
	v_xor_b32_e32 v248, v248, v237
	v_lshl_add_u32 v237, s16, 4, v237
	v_lshlrev_b32_e32 v237, 11, v237
	v_lshl_add_u32 v237, v248, 4, v237
	s_add_u32 m0, s49, 69632
	s_nop 0
	global_load_lds_dwordx4 v237, s[44:45]
	v_lshrrev_b32_e32 v237, 5, v236
	v_add_u32_e32 v237, 10, v237
	v_and_b32_e32 v248, 31, v236
	v_xor_b32_e32 v248, v248, v237
	v_lshl_add_u32 v237, s16, 4, v237
	v_lshlrev_b32_e32 v237, 11, v237
	v_lshl_add_u32 v237, v248, 4, v237
	s_add_u32 m0, s49, 70656
	s_nop 0
	global_load_lds_dwordx4 v237, s[44:45]
	v_lshrrev_b32_e32 v237, 5, v236
	v_add_u32_e32 v237, 12, v237
	v_and_b32_e32 v248, 31, v236
	v_xor_b32_e32 v248, v248, v237
	v_lshl_add_u32 v237, s16, 4, v237
	v_lshlrev_b32_e32 v237, 11, v237
	v_lshl_add_u32 v237, v248, 4, v237
; #define LAS __attribute__((address_space(3)))
; #define MFMA16(a, b, c) __builtin_amdgcn_mfma_f32_16x16x32_bf16((a), (b), (c), 0, 0, 0)
; #define DSEC(k) do { if (PROBE_DSEC) { const unsigned long long tn_ = __builtin_amdgcn_s_memrealtime(); if (PROBE_DSEC == (k)) tsec += tn_ - tl_; tl_ = tn_; } } while (0)
; #define XV_LOAD(R, b_, h_, hh_) do { _Pragma("unroll") for (int i = 0; i < 8; ++i) { const int p = tid + 512 * i, dhr = p >> 5, c = p & 31; R[i] = *(const u32x4*)(memVT + (size_t)((h_) * 256 + 128 * (hh_) + dhr) * MROWS + (b_) * NMEM + 8 * c); } } while (0)
; #define XV_WRITE(R) do { _Pragma("unroll") for (int i = 0; i < 8; ++i) { const int p = tid + 512 * i, dhr = p >> 5, c = p & 31; u32x2 lo, hi; lo.x = R[i].x; lo.y = R[i].y; hi.x = R[i].z; hi.y = R[i].w; \
;         *(LAS u32x2*)(VL + vt_off(dhr, 2 * c)) = lo; *(LAS u32x2*)(VL + vt_off(dhr, 2 * c + 1)) = hi; } } while (0)
; DI void xattn_phase(LAS unsigned char* L, const bf16* Qx, const bf16* memK, const bf16* memVT, bf16* Ox, int G, int bid, int tid, unsigned long long& tsec) {
;     ...
;         for (int hh = 0; hh < 2; ++hh) {
;             if (hh == 1) { DSEC(14); __syncthreads(); XV_WRITE(rb); XV_LOAD(rb, bn, hn, 0); __syncthreads(); DSEC(15); }
;             f32x4 o[8];
; #pragma unroll
;             for (int dt = 0; dt < 8; ++dt) o[dt] = (f32x4){0.f, 0.f, 0.f, 0.f};
;             const unsigned x0 = (unsigned)(fq ^ (fr >> 3));
;             const LAS unsigned char* vev = L + KL_BYTES + fr * VSTR + (x0 << 3); const LAS unsigned char* vod = L + KL_BYTES + fr * VSTR + ((x0 ^ 2u) << 3);
; #pragma unroll
;             for (int pp = 0; pp < 8; ++pp)
; #pragma unroll
;                 for (int d4 = 0; d4 < 2; ++d4) { bf16x8 vf[4];
; #pragma unroll
;                     for (int dq = 0; dq < 4; ++dq) { const int dt = 4 * d4 + dq; const LAS unsigned char* vb_ = ((dt & 1) ? vod : vev) + 16 * dt * VSTR + 64 * pp;
;                         const s16x4 lo = *(const LAS s16x4*)(vb_ + (((2 * dt) & 4) << 3)), hi = *(const LAS s16x4*)(vb_ + ((((2 * dt) & 4) ^ 4) << 3)); vf[dq] = __builtin_shufflevector(lo, hi, 0, 1, 2, 3, 4, 5, 6, 7); }
; #pragma unroll
;                     for (int dq = 0; dq < 4; ++dq) o[4 * d4 + dq] = MFMA16(vf[dq], pf[pp], o[4 * d4 + dq]);
;                 }
	s_add_u32 m0, s49, 71680
	s_nop 0
	global_load_lds_dwordx4 v237, s[44:45]
	v_lshrrev_b32_e32 v237, 5, v236
	v_add_u32_e32 v237, 14, v237
	v_and_b32_e32 v248, 31, v236
	v_xor_b32_e32 v248, v248, v237
	v_lshl_add_u32 v237, s16, 4, v237
	v_lshlrev_b32_e32 v237, 11, v237
	v_lshl_add_u32 v237, v248, 4, v237
	s_add_u32 m0, s49, 72704
	s_nop 0
	global_load_lds_dwordx4 v237, s[44:45]
	ds_read_b64 v[98:99], v216 offset:0
	ds_read_b64 v[100:101], v217 offset:0
	ds_read_b64 v[102:103], v216 offset:8192
	ds_read_b64 v[104:105], v217 offset:8192
	ds_read_b64 v[106:107], v216 offset:16384
	ds_read_b64 v[108:109], v217 offset:16384
	ds_read_b64 v[110:111], v216 offset:24576
	ds_read_b64 v[112:113], v217 offset:24576
	ds_read_b64 v[114:115], v216 offset:32768
	ds_read_b64 v[116:117], v217 offset:32768
	ds_read_b64 v[118:119], v216 offset:40960
	ds_read_b64 v[120:121], v217 offset:40960
	ds_read_b64 v[122:123], v216 offset:49152
	ds_read_b64 v[124:125], v217 offset:49152
	ds_read_b64 v[126:127], v216 offset:57344
	ds_read_b64 v[128:129], v217 offset:57344
	ds_read_b64 v[130:131], v218 offset:0
	ds_read_b64 v[132:133], v219 offset:0
	ds_read_b64 v[134:135], v218 offset:8192
	ds_read_b64 v[136:137], v219 offset:8192
	ds_read_b64 v[138:139], v218 offset:16384
	ds_read_b64 v[140:141], v219 offset:16384
	ds_read_b64 v[142:143], v218 offset:24576
	ds_read_b64 v[144:145], v219 offset:24576
	ds_read_b64 v[146:147], v218 offset:32768
	ds_read_b64 v[148:149], v219 offset:32768
	ds_read_b64 v[150:151], v218 offset:40960
	ds_read_b64 v[152:153], v219 offset:40960
	ds_read_b64 v[154:155], v218 offset:49152
	ds_read_b64 v[156:157], v219 offset:49152
	ds_read_b64 v[158:159], v218 offset:57344
	ds_read_b64 v[160:161], v219 offset:57344
	s_waitcnt lgkmcnt(15)
	v_mfma_f32_16x16x32_bf16 v[2:5], v[98:101], v[162:165], 0
	ds_read_b64 v[98:99], v220 offset:0
	ds_read_b64 v[100:101], v221 offset:0
	v_mfma_f32_16x16x32_bf16 v[6:9], v[102:105], v[162:165], 0
	ds_read_b64 v[102:103], v220 offset:8192
	ds_read_b64 v[104:105], v221 offset:8192
	v_mfma_f32_16x16x32_bf16 v[10:13], v[106:109], v[162:165], 0
	ds_read_b64 v[106:107], v220 offset:16384
	ds_read_b64 v[108:109], v221 offset:16384
	v_mfma_f32_16x16x32_bf16 v[14:17], v[110:113], v[162:165], 0
	ds_read_b64 v[110:111], v220 offset:24576
	ds_read_b64 v[112:113], v221 offset:24576
	v_mfma_f32_16x16x32_bf16 v[18:21], v[114:117], v[162:165], 0
	ds_read_b64 v[114:115], v220 offset:32768
	ds_read_b64 v[116:117], v221 offset:32768
	v_mfma_f32_16x16x32_bf16 v[22:25], v[118:121], v[162:165], 0
	ds_read_b64 v[118:119], v220 offset:40960
	ds_read_b64 v[120:121], v221 offset:40960
	v_mfma_f32_16x16x32_bf16 v[26:29], v[122:125], v[162:165], 0
	ds_read_b64 v[122:123], v220 offset:49152
	ds_read_b64 v[124:125], v221 offset:49152
	v_mfma_f32_16x16x32_bf16 v[30:33], v[126:129], v[162:165], 0
	ds_read_b64 v[126:127], v220 offset:57344
	ds_read_b64 v[128:129], v221 offset:57344
	s_waitcnt lgkmcnt(15)
	v_mfma_f32_16x16x32_bf16 v[2:5], v[130:133], v[166:169], v[2:5]
	ds_read_b64 v[130:131], v222 offset:0
	ds_read_b64 v[132:133], v223 offset:0
	v_mfma_f32_16x16x32_bf16 v[6:9], v[134:137], v[166:169], v[6:9]
	ds_read_b64 v[134:135], v222 offset:8192
	ds_read_b64 v[136:137], v223 offset:8192
	v_mfma_f32_16x16x32_bf16 v[10:13], v[138:141], v[166:169], v[10:13]
	ds_read_b64 v[138:139], v222 offset:16384
	ds_read_b64 v[140:141], v223 offset:16384
	v_mfma_f32_16x16x32_bf16 v[14:17], v[142:145], v[166:169], v[14:17]
	ds_read_b64 v[142:143], v222 offset:24576
	ds_read_b64 v[144:145], v223 offset:24576
	v_mfma_f32_16x16x32_bf16 v[18:21], v[146:149], v[166:169], v[18:21]
	ds_read_b64 v[146:147], v222 offset:32768
	ds_read_b64 v[148:149], v223 offset:32768
	v_mfma_f32_16x16x32_bf16 v[22:25], v[150:153], v[166:169], v[22:25]
	ds_read_b64 v[150:151], v222 offset:40960
	ds_read_b64 v[152:153], v223 offset:40960
	v_mfma_f32_16x16x32_bf16 v[26:29], v[154:157], v[166:169], v[26:29]
	ds_read_b64 v[154:155], v222 offset:49152
	ds_read_b64 v[156:157], v223 offset:49152
	v_mfma_f32_16x16x32_bf16 v[30:33], v[158:161], v[166:169], v[30:33]
	ds_read_b64 v[158:159], v222 offset:57344
	ds_read_b64 v[160:161], v223 offset:57344
	s_waitcnt lgkmcnt(15)
	v_mfma_f32_16x16x32_bf16 v[2:5], v[98:101], v[170:173], v[2:5]
	ds_read_b64 v[98:99], v216 offset:256
	ds_read_b64 v[100:101], v217 offset:256
	v_mfma_f32_16x16x32_bf16 v[6:9], v[102:105], v[170:173], v[6:9]
	ds_read_b64 v[102:103], v216 offset:8448
	ds_read_b64 v[104:105], v217 offset:8448
	v_mfma_f32_16x16x32_bf16 v[10:13], v[106:109], v[170:173], v[10:13]
	ds_read_b64 v[106:107], v216 offset:16640
	ds_read_b64 v[108:109], v217 offset:16640
	v_mfma_f32_16x16x32_bf16 v[14:17], v[110:113], v[170:173], v[14:17]
	ds_read_b64 v[110:111], v216 offset:24832
	ds_read_b64 v[112:113], v217 offset:24832
	v_mfma_f32_16x16x32_bf16 v[18:21], v[114:117], v[170:173], v[18:21]
	ds_read_b64 v[114:115], v216 offset:33024
	ds_read_b64 v[116:117], v217 offset:33024
	v_mfma_f32_16x16x32_bf16 v[22:25], v[118:121], v[170:173], v[22:25]
	ds_read_b64 v[118:119], v216 offset:41216
	ds_read_b64 v[120:121], v217 offset:41216
	v_mfma_f32_16x16x32_bf16 v[26:29], v[122:125], v[170:173], v[26:29]
	ds_read_b64 v[122:123], v216 offset:49408
	ds_read_b64 v[124:125], v217 offset:49408
	v_mfma_f32_16x16x32_bf16 v[30:33], v[126:129], v[170:173], v[30:33]
	ds_read_b64 v[126:127], v216 offset:57600
	ds_read_b64 v[128:129], v217 offset:57600
	s_waitcnt lgkmcnt(15)
; #define LAS __attribute__((address_space(3)))
; #define MFMA16(a, b, c) __builtin_amdgcn_mfma_f32_16x16x32_bf16((a), (b), (c), 0, 0, 0)
; DI void xattn_phase(LAS unsigned char* L, const bf16* Qx, const bf16* memK, const bf16* memVT, bf16* Ox, int G, int bid, int tid, unsigned long long& tsec) {
;     ...
;     for (int unit = bid; unit < 512; unit += G) {
;         const int j = unit & 31, h = (unit >> 5) & 3, b = unit >> 7;
;         const int nun = unit + G < 512 ? unit + G : unit, hn = (nun >> 5) & 3, bn = nun >> 7;
;     ...
;             for (int pp = 0; pp < 8; ++pp)
; #pragma unroll
;                 for (int d4 = 0; d4 < 2; ++d4) { bf16x8 vf[4];
; #pragma unroll
;                     for (int dq = 0; dq < 4; ++dq) { const int dt = 4 * d4 + dq; const LAS unsigned char* vb_ = ((dt & 1) ? vod : vev) + 16 * dt * VSTR + 64 * pp;
;                         const s16x4 lo = *(const LAS s16x4*)(vb_ + (((2 * dt) & 4) << 3)), hi = *(const LAS s16x4*)(vb_ + ((((2 * dt) & 4) ^ 4) << 3)); vf[dq] = __builtin_shufflevector(lo, hi, 0, 1, 2, 3, 4, 5, 6, 7); }
; #pragma unroll
;                     for (int dq = 0; dq < 4; ++dq) o[4 * d4 + dq] = MFMA16(vf[dq], pf[pp], o[4 * d4 + dq]);
;                 }
	v_mfma_f32_16x16x32_bf16 v[2:5], v[130:133], v[174:177], v[2:5]
	ds_read_b64 v[130:131], v218 offset:256
	ds_read_b64 v[132:133], v219 offset:256
	v_mfma_f32_16x16x32_bf16 v[6:9], v[134:137], v[174:177], v[6:9]
	ds_read_b64 v[134:135], v218 offset:8448
	ds_read_b64 v[136:137], v219 offset:8448
	v_mfma_f32_16x16x32_bf16 v[10:13], v[138:141], v[174:177], v[10:13]
	ds_read_b64 v[138:139], v218 offset:16640
	ds_read_b64 v[140:141], v219 offset:16640
	v_mfma_f32_16x16x32_bf16 v[14:17], v[142:145], v[174:177], v[14:17]
	ds_read_b64 v[142:143], v218 offset:24832
	ds_read_b64 v[144:145], v219 offset:24832
	v_mfma_f32_16x16x32_bf16 v[18:21], v[146:149], v[174:177], v[18:21]
	ds_read_b64 v[146:147], v218 offset:33024
	ds_read_b64 v[148:149], v219 offset:33024
	v_mfma_f32_16x16x32_bf16 v[22:25], v[150:153], v[174:177], v[22:25]
	ds_read_b64 v[150:151], v218 offset:41216
	ds_read_b64 v[152:153], v219 offset:41216
	v_mfma_f32_16x16x32_bf16 v[26:29], v[154:157], v[174:177], v[26:29]
	ds_read_b64 v[154:155], v218 offset:49408
	ds_read_b64 v[156:157], v219 offset:49408
	v_mfma_f32_16x16x32_bf16 v[30:33], v[158:161], v[174:177], v[30:33]
	ds_read_b64 v[158:159], v218 offset:57600
	ds_read_b64 v[160:161], v219 offset:57600
	s_waitcnt lgkmcnt(15)
	v_mfma_f32_16x16x32_bf16 v[2:5], v[98:101], v[178:181], v[2:5]
	ds_read_b64 v[98:99], v220 offset:256
	ds_read_b64 v[100:101], v221 offset:256
	v_mfma_f32_16x16x32_bf16 v[6:9], v[102:105], v[178:181], v[6:9]
	ds_read_b64 v[102:103], v220 offset:8448
	ds_read_b64 v[104:105], v221 offset:8448
	v_mfma_f32_16x16x32_bf16 v[10:13], v[106:109], v[178:181], v[10:13]
	ds_read_b64 v[106:107], v220 offset:16640
	ds_read_b64 v[108:109], v221 offset:16640
	v_mfma_f32_16x16x32_bf16 v[14:17], v[110:113], v[178:181], v[14:17]
	ds_read_b64 v[110:111], v220 offset:24832
	ds_read_b64 v[112:113], v221 offset:24832
	v_mfma_f32_16x16x32_bf16 v[18:21], v[114:117], v[178:181], v[18:21]
	ds_read_b64 v[114:115], v220 offset:33024
	ds_read_b64 v[116:117], v221 offset:33024
	v_mfma_f32_16x16x32_bf16 v[22:25], v[118:121], v[178:181], v[22:25]
	ds_read_b64 v[118:119], v220 offset:41216
	ds_read_b64 v[120:121], v221 offset:41216
	v_mfma_f32_16x16x32_bf16 v[26:29], v[122:125], v[178:181], v[26:29]
	ds_read_b64 v[122:123], v220 offset:49408
	ds_read_b64 v[124:125], v221 offset:49408
	v_mfma_f32_16x16x32_bf16 v[30:33], v[126:129], v[178:181], v[30:33]
	ds_read_b64 v[126:127], v220 offset:57600
	ds_read_b64 v[128:129], v221 offset:57600
	s_waitcnt lgkmcnt(15)
	v_mfma_f32_16x16x32_bf16 v[2:5], v[130:133], v[182:185], v[2:5]
	ds_read_b64 v[130:131], v222 offset:256
	ds_read_b64 v[132:133], v223 offset:256
	v_mfma_f32_16x16x32_bf16 v[6:9], v[134:137], v[182:185], v[6:9]
	ds_read_b64 v[134:135], v222 offset:8448
	ds_read_b64 v[136:137], v223 offset:8448
	v_mfma_f32_16x16x32_bf16 v[10:13], v[138:141], v[182:185], v[10:13]
	ds_read_b64 v[138:139], v222 offset:16640
	ds_read_b64 v[140:141], v223 offset:16640
	v_mfma_f32_16x16x32_bf16 v[14:17], v[142:145], v[182:185], v[14:17]
	ds_read_b64 v[142:143], v222 offset:24832
	ds_read_b64 v[144:145], v223 offset:24832
	v_mfma_f32_16x16x32_bf16 v[18:21], v[146:149], v[182:185], v[18:21]
	ds_read_b64 v[146:147], v222 offset:33024
	ds_read_b64 v[148:149], v223 offset:33024
	v_mfma_f32_16x16x32_bf16 v[22:25], v[150:153], v[182:185], v[22:25]
	ds_read_b64 v[150:151], v222 offset:41216
	ds_read_b64 v[152:153], v223 offset:41216
	v_mfma_f32_16x16x32_bf16 v[26:29], v[154:157], v[182:185], v[26:29]
	ds_read_b64 v[154:155], v222 offset:49408
	ds_read_b64 v[156:157], v223 offset:49408
	v_mfma_f32_16x16x32_bf16 v[30:33], v[158:161], v[182:185], v[30:33]
	ds_read_b64 v[158:159], v222 offset:57600
	ds_read_b64 v[160:161], v223 offset:57600
	s_waitcnt lgkmcnt(15)
	v_mfma_f32_16x16x32_bf16 v[2:5], v[98:101], v[186:189], v[2:5]
	v_mfma_f32_16x16x32_bf16 v[6:9], v[102:105], v[186:189], v[6:9]
	v_mfma_f32_16x16x32_bf16 v[10:13], v[106:109], v[186:189], v[10:13]
	v_mfma_f32_16x16x32_bf16 v[14:17], v[110:113], v[186:189], v[14:17]
	v_mfma_f32_16x16x32_bf16 v[18:21], v[114:117], v[186:189], v[18:21]
	v_mfma_f32_16x16x32_bf16 v[22:25], v[118:121], v[186:189], v[22:25]
	v_mfma_f32_16x16x32_bf16 v[26:29], v[122:125], v[186:189], v[26:29]
	v_mfma_f32_16x16x32_bf16 v[30:33], v[126:129], v[186:189], v[30:33]
	s_waitcnt lgkmcnt(0)
	v_mfma_f32_16x16x32_bf16 v[2:5], v[130:133], v[190:193], v[2:5]
	v_mfma_f32_16x16x32_bf16 v[6:9], v[134:137], v[190:193], v[6:9]
	v_mfma_f32_16x16x32_bf16 v[10:13], v[138:141], v[190:193], v[10:13]
	v_mfma_f32_16x16x32_bf16 v[14:17], v[142:145], v[190:193], v[14:17]
	v_mfma_f32_16x16x32_bf16 v[18:21], v[146:149], v[190:193], v[18:21]
	v_mfma_f32_16x16x32_bf16 v[22:25], v[150:153], v[190:193], v[22:25]
	v_mfma_f32_16x16x32_bf16 v[26:29], v[154:157], v[190:193], v[26:29]
	v_mfma_f32_16x16x32_bf16 v[30:33], v[158:161], v[190:193], v[30:33]
	s_waitcnt vmcnt(0)
	s_barrier
	s_add_u32 s18, s17, 32
	s_bitcmp1_b32 s18, 5
	s_cbranch_scc0 .Lxa_last
; #define LAS __attribute__((address_space(3)))
; #define MFMA16(a, b, c) __builtin_amdgcn_mfma_f32_16x16x32_bf16((a), (b), (c), 0, 0, 0)
; #define DSEC(k) do { if (PROBE_DSEC) { const unsigned long long tn_ = __builtin_amdgcn_s_memrealtime(); if (PROBE_DSEC == (k)) tsec += tn_ - tl_; tl_ = tn_; } } while (0)
; DI void xattn_phase(LAS unsigned char* L, const bf16* Qx, const bf16* memK, const bf16* memVT, bf16* Ox, int G, int bid, int tid, unsigned long long& tsec) {
;     ...
;     for (int unit = bid; unit < 512; unit += G) {
;         const int j = unit & 31, h = (unit >> 5) & 3, b = unit >> 7;
;         const int nun = unit + G < 512 ? unit + G : unit, hn = (nun >> 5) & 3, bn = nun >> 7;
;         asm volatile("" : "+v"(ra[0]), "+v"(ra[1]), "+v"(ra[2]), "+v"(ra[3]), "+v"(ra[4]), "+v"(ra[5]), "+v"(ra[6]), "+v"(ra[7]));
;         asm volatile("" : "+v"(rb[0]), "+v"(rb[1]), "+v"(rb[2]), "+v"(rb[3]), "+v"(rb[4]), "+v"(rb[5]), "+v"(rb[6]), "+v"(rb[7]));
;         const int tok0 = b * T + 128 * j; const size_t tq = (size_t)(tok0 + 16 * wid + fr);
;     ...
;             if (hh == 1) { DSEC(14); __syncthreads(); XV_WRITE(rb); XV_LOAD(rb, bn, hn, 0); __syncthreads(); DSEC(15); }
;             f32x4 o[8];
; #pragma unroll
;             for (int dt = 0; dt < 8; ++dt) o[dt] = (f32x4){0.f, 0.f, 0.f, 0.f};
;             const unsigned x0 = (unsigned)(fq ^ (fr >> 3));
;             const LAS unsigned char* vev = L + KL_BYTES + fr * VSTR + (x0 << 3); const LAS unsigned char* vod = L + KL_BYTES + fr * VSTR + ((x0 ^ 2u) << 3);
; #pragma unroll
;             for (int pp = 0; pp < 8; ++pp)
; #pragma unroll
;                 for (int d4 = 0; d4 < 2; ++d4) { bf16x8 vf[4];
; #pragma unroll
;                     for (int dq = 0; dq < 4; ++dq) { const int dt = 4 * d4 + dq; const LAS unsigned char* vb_ = ((dt & 1) ? vod : vev) + 16 * dt * VSTR + 64 * pp;
;                         const s16x4 lo = *(const LAS s16x4*)(vb_ + (((2 * dt) & 4) << 3)), hi = *(const LAS s16x4*)(vb_ + ((((2 * dt) & 4) ^ 4) << 3)); vf[dq] = __builtin_shufflevector(lo, hi, 0, 1, 2, 3, 4, 5, 6, 7); }
; #pragma unroll
;                     for (int dq = 0; dq < 4; ++dq) o[4 * d4 + dq] = MFMA16(vf[dq], pf[pp], o[4 * d4 + dq]);
;                 }
	s_and_b32 s44, s18, 31
	s_bfe_u32 s45, s18, 0x20005
	s_lshr_b32 s46, s18, 7
	s_lshl_b32 s47, s46, 12
	s_lshl_b32 s44, s44, 7
	s_add_u32 s47, s47, s44
	s_lshl_b32 s47, s47, 11
	s_lshl_b32 s44, s45, 9
	s_add_u32 s47, s47, s44
	s_add_u32 s20, s0, s47
	s_addc_u32 s21, s1, 0
	s_lshl_b32 s47, s46, 19
	s_add_u32 s47, s47, s44
	s_add_u32 s24, s36, s47
	s_addc_u32 s25, s37, 0
	s_lshl_b32 s47, s45, 19
	s_lshl_b32 s44, s46, 9
	s_add_u32 s47, s47, s44
	s_add_u32 s42, s2, s47
	s_addc_u32 s43, s3, 0
	s_add_u32 s44, s24, 0
	s_addc_u32 s45, s25, 0
	s_add_u32 s46, s44, 0x8000
	s_addc_u32 s47, s45, 0
	s_add_u32 m0, s49, 0
	s_nop 0
	global_load_lds_dwordx4 v198, s[44:45]
	s_add_u32 m0, s49, 1024
	s_nop 0
	global_load_lds_dwordx4 v199, s[44:45]
	s_add_u32 m0, s49, 2048
	s_nop 0
	global_load_lds_dwordx4 v200, s[44:45]
	s_add_u32 m0, s49, 3072
	s_nop 0
	global_load_lds_dwordx4 v201, s[44:45]
	s_add_u32 m0, s49, 4096
	s_nop 0
	global_load_lds_dwordx4 v198, s[46:47]
	s_add_u32 m0, s49, 5120
	s_nop 0
	global_load_lds_dwordx4 v199, s[46:47]
	s_add_u32 m0, s49, 6144
	s_nop 0
	global_load_lds_dwordx4 v200, s[46:47]
	s_add_u32 m0, s49, 7168
	s_nop 0
	global_load_lds_dwordx4 v201, s[46:47]
	global_load_dwordx4 v[66:69], v232, s[20:21]
	global_load_dwordx4 v[70:73], v232, s[20:21] offset:64
	global_load_dwordx4 v[74:77], v232, s[20:21] offset:128
	global_load_dwordx4 v[78:81], v232, s[20:21] offset:192
	global_load_dwordx4 v[82:85], v232, s[20:21] offset:256
	global_load_dwordx4 v[86:89], v232, s[20:21] offset:320
	global_load_dwordx4 v[90:93], v232, s[20:21] offset:384
	global_load_dwordx4 v[94:97], v232, s[20:21] offset:448
	s_lshl_b32 s46, s16, 1
	s_add_u32 s46, s46, 0
	v_lshl_add_u32 v237, s46, 6, v236
	v_lshrrev_b32_e32 v248, 2, v237
	v_and_b32_e32 v237, 3, v237
	v_lshlrev_b32_e32 v237, 6, v237
	v_lshl_add_u32 v237, v248, 11, v237
	global_load_dword v249, v237, s[24:25] offset:256
	s_lshl_b32 s46, s16, 1
	s_add_u32 s46, s46, 1
	v_lshl_add_u32 v237, s46, 6, v236
	v_lshrrev_b32_e32 v248, 2, v237
	v_and_b32_e32 v237, 3, v237
	v_lshlrev_b32_e32 v237, 6, v237
	v_lshl_add_u32 v237, v248, 11, v237
	global_load_dword v249, v237, s[24:25] offset:256
	s_lshl_b32 s46, s16, 2
	s_add_u32 s46, s46, 0
	v_lshl_add_u32 v237, s46, 6, v236
	v_lshrrev_b32_e32 v248, 3, v237
	v_and_b32_e32 v237, 7, v237
	v_lshlrev_b32_e32 v237, 6, v237
	v_lshl_add_u32 v237, v248, 11, v237
	global_load_dword v249, v237, s[42:43]
	s_lshl_b32 s46, s16, 2
	s_add_u32 s46, s46, 1
	v_lshl_add_u32 v237, s46, 6, v236
	v_lshrrev_b32_e32 v248, 3, v237
	v_and_b32_e32 v237, 7, v237
	v_lshlrev_b32_e32 v237, 6, v237
	v_lshl_add_u32 v237, v248, 11, v237
	global_load_dword v249, v237, s[42:43]
	s_lshl_b32 s46, s16, 2
	s_add_u32 s46, s46, 2
	v_lshl_add_u32 v237, s46, 6, v236
	v_lshrrev_b32_e32 v248, 3, v237
	v_and_b32_e32 v237, 7, v237
	v_lshlrev_b32_e32 v237, 6, v237
	v_lshl_add_u32 v237, v248, 11, v237
	global_load_dword v249, v237, s[42:43]
	s_lshl_b32 s46, s16, 2
	s_add_u32 s46, s46, 3
	v_lshl_add_u32 v237, s46, 6, v236
	v_lshrrev_b32_e32 v248, 3, v237
	v_and_b32_e32 v237, 7, v237
	v_lshlrev_b32_e32 v237, 6, v237
	v_lshl_add_u32 v237, v248, 11, v237
	global_load_dword v249, v237, s[42:43]
	ds_read_b64 v[98:99], v224 offset:0
	ds_read_b64 v[100:101], v225 offset:0
	ds_read_b64 v[102:103], v224 offset:8192
	ds_read_b64 v[104:105], v225 offset:8192
	ds_read_b64 v[106:107], v224 offset:16384
	ds_read_b64 v[108:109], v225 offset:16384
	ds_read_b64 v[110:111], v224 offset:24576
	ds_read_b64 v[112:113], v225 offset:24576
	ds_read_b64 v[114:115], v224 offset:32768
	ds_read_b64 v[116:117], v225 offset:32768
	ds_read_b64 v[118:119], v224 offset:40960
	ds_read_b64 v[120:121], v225 offset:40960
	ds_read_b64 v[122:123], v224 offset:49152
	ds_read_b64 v[124:125], v225 offset:49152
	ds_read_b64 v[126:127], v224 offset:57344
	ds_read_b64 v[128:129], v225 offset:57344
	ds_read_b64 v[130:131], v226 offset:0
	ds_read_b64 v[132:133], v227 offset:0
	ds_read_b64 v[134:135], v226 offset:8192
	ds_read_b64 v[136:137], v227 offset:8192
	ds_read_b64 v[138:139], v226 offset:16384
	ds_read_b64 v[140:141], v227 offset:16384
	ds_read_b64 v[142:143], v226 offset:24576
	ds_read_b64 v[144:145], v227 offset:24576
	ds_read_b64 v[146:147], v226 offset:32768
	ds_read_b64 v[148:149], v227 offset:32768
	ds_read_b64 v[150:151], v226 offset:40960
	ds_read_b64 v[152:153], v227 offset:40960
	ds_read_b64 v[154:155], v226 offset:49152
	ds_read_b64 v[156:157], v227 offset:49152
	ds_read_b64 v[158:159], v226 offset:57344
	ds_read_b64 v[160:161], v227 offset:57344
	s_waitcnt lgkmcnt(15)
	v_mfma_f32_16x16x32_bf16 v[34:37], v[98:101], v[162:165], 0
	ds_read_b64 v[98:99], v228 offset:0
	ds_read_b64 v[100:101], v229 offset:0
	v_mfma_f32_16x16x32_bf16 v[38:41], v[102:105], v[162:165], 0
	ds_read_b64 v[102:103], v228 offset:8192
	ds_read_b64 v[104:105], v229 offset:8192
	v_mfma_f32_16x16x32_bf16 v[42:45], v[106:109], v[162:165], 0
	ds_read_b64 v[106:107], v228 offset:16384
	ds_read_b64 v[108:109], v229 offset:16384
	v_mfma_f32_16x16x32_bf16 v[46:49], v[110:113], v[162:165], 0
	ds_read_b64 v[110:111], v228 offset:24576
	ds_read_b64 v[112:113], v229 offset:24576
	v_mfma_f32_16x16x32_bf16 v[50:53], v[114:117], v[162:165], 0
	ds_read_b64 v[114:115], v228 offset:32768
	ds_read_b64 v[116:117], v229 offset:32768
	v_mfma_f32_16x16x32_bf16 v[54:57], v[118:121], v[162:165], 0
	ds_read_b64 v[118:119], v228 offset:40960
	ds_read_b64 v[120:121], v229 offset:40960
	v_mfma_f32_16x16x32_bf16 v[58:61], v[122:125], v[162:165], 0
	ds_read_b64 v[122:123], v228 offset:49152
	ds_read_b64 v[124:125], v229 offset:49152
	v_mfma_f32_16x16x32_bf16 v[62:65], v[126:129], v[162:165], 0
	ds_read_b64 v[126:127], v228 offset:57344
	ds_read_b64 v[128:129], v229 offset:57344
	s_waitcnt lgkmcnt(15)
; #define LAS __attribute__((address_space(3)))
; #define MFMA16(a, b, c) __builtin_amdgcn_mfma_f32_16x16x32_bf16((a), (b), (c), 0, 0, 0)
; DI void xattn_phase(LAS unsigned char* L, const bf16* Qx, const bf16* memK, const bf16* memVT, bf16* Ox, int G, int bid, int tid, unsigned long long& tsec) {
;     ...
;             for (int pp = 0; pp < 8; ++pp)
; #pragma unroll
;                 for (int d4 = 0; d4 < 2; ++d4) { bf16x8 vf[4];
; #pragma unroll
;                     for (int dq = 0; dq < 4; ++dq) { const int dt = 4 * d4 + dq; const LAS unsigned char* vb_ = ((dt & 1) ? vod : vev) + 16 * dt * VSTR + 64 * pp;
;                         const s16x4 lo = *(const LAS s16x4*)(vb_ + (((2 * dt) & 4) << 3)), hi = *(const LAS s16x4*)(vb_ + ((((2 * dt) & 4) ^ 4) << 3)); vf[dq] = __builtin_shufflevector(lo, hi, 0, 1, 2, 3, 4, 5, 6, 7); }
; #pragma unroll
;                     for (int dq = 0; dq < 4; ++dq) o[4 * d4 + dq] = MFMA16(vf[dq], pf[pp], o[4 * d4 + dq]);
;                 }
	v_mfma_f32_16x16x32_bf16 v[34:37], v[130:133], v[166:169], v[34:37]
	ds_read_b64 v[130:131], v230 offset:0
	ds_read_b64 v[132:133], v231 offset:0
	v_mfma_f32_16x16x32_bf16 v[38:41], v[134:137], v[166:169], v[38:41]
	ds_read_b64 v[134:135], v230 offset:8192
	ds_read_b64 v[136:137], v231 offset:8192
	v_mfma_f32_16x16x32_bf16 v[42:45], v[138:141], v[166:169], v[42:45]
	ds_read_b64 v[138:139], v230 offset:16384
	ds_read_b64 v[140:141], v231 offset:16384
	v_mfma_f32_16x16x32_bf16 v[46:49], v[142:145], v[166:169], v[46:49]
	ds_read_b64 v[142:143], v230 offset:24576
	ds_read_b64 v[144:145], v231 offset:24576
	v_mfma_f32_16x16x32_bf16 v[50:53], v[146:149], v[166:169], v[50:53]
	ds_read_b64 v[146:147], v230 offset:32768
	ds_read_b64 v[148:149], v231 offset:32768
	v_mfma_f32_16x16x32_bf16 v[54:57], v[150:153], v[166:169], v[54:57]
	ds_read_b64 v[150:151], v230 offset:40960
	ds_read_b64 v[152:153], v231 offset:40960
	v_mfma_f32_16x16x32_bf16 v[58:61], v[154:157], v[166:169], v[58:61]
	ds_read_b64 v[154:155], v230 offset:49152
	ds_read_b64 v[156:157], v231 offset:49152
	v_mfma_f32_16x16x32_bf16 v[62:65], v[158:161], v[166:169], v[62:65]
	ds_read_b64 v[158:159], v230 offset:57344
	ds_read_b64 v[160:161], v231 offset:57344
	s_waitcnt lgkmcnt(15)
	v_mfma_f32_16x16x32_bf16 v[34:37], v[98:101], v[170:173], v[34:37]
	ds_read_b64 v[98:99], v224 offset:256
	ds_read_b64 v[100:101], v225 offset:256
	v_mfma_f32_16x16x32_bf16 v[38:41], v[102:105], v[170:173], v[38:41]
	ds_read_b64 v[102:103], v224 offset:8448
	ds_read_b64 v[104:105], v225 offset:8448
	v_mfma_f32_16x16x32_bf16 v[42:45], v[106:109], v[170:173], v[42:45]
	ds_read_b64 v[106:107], v224 offset:16640
	ds_read_b64 v[108:109], v225 offset:16640
	v_mfma_f32_16x16x32_bf16 v[46:49], v[110:113], v[170:173], v[46:49]
	ds_read_b64 v[110:111], v224 offset:24832
	ds_read_b64 v[112:113], v225 offset:24832
	v_mfma_f32_16x16x32_bf16 v[50:53], v[114:117], v[170:173], v[50:53]
	ds_read_b64 v[114:115], v224 offset:33024
	ds_read_b64 v[116:117], v225 offset:33024
	v_mfma_f32_16x16x32_bf16 v[54:57], v[118:121], v[170:173], v[54:57]
	ds_read_b64 v[118:119], v224 offset:41216
	ds_read_b64 v[120:121], v225 offset:41216
	v_mfma_f32_16x16x32_bf16 v[58:61], v[122:125], v[170:173], v[58:61]
	ds_read_b64 v[122:123], v224 offset:49408
	ds_read_b64 v[124:125], v225 offset:49408
	v_mfma_f32_16x16x32_bf16 v[62:65], v[126:129], v[170:173], v[62:65]
	ds_read_b64 v[126:127], v224 offset:57600
	ds_read_b64 v[128:129], v225 offset:57600
	s_waitcnt lgkmcnt(15)
	v_mfma_f32_16x16x32_bf16 v[34:37], v[130:133], v[174:177], v[34:37]
	ds_read_b64 v[130:131], v226 offset:256
	ds_read_b64 v[132:133], v227 offset:256
	v_mfma_f32_16x16x32_bf16 v[38:41], v[134:137], v[174:177], v[38:41]
	ds_read_b64 v[134:135], v226 offset:8448
	ds_read_b64 v[136:137], v227 offset:8448
	v_mfma_f32_16x16x32_bf16 v[42:45], v[138:141], v[174:177], v[42:45]
	ds_read_b64 v[138:139], v226 offset:16640
	ds_read_b64 v[140:141], v227 offset:16640
	v_mfma_f32_16x16x32_bf16 v[46:49], v[142:145], v[174:177], v[46:49]
	ds_read_b64 v[142:143], v226 offset:24832
	ds_read_b64 v[144:145], v227 offset:24832
	v_mfma_f32_16x16x32_bf16 v[50:53], v[146:149], v[174:177], v[50:53]
	ds_read_b64 v[146:147], v226 offset:33024
	ds_read_b64 v[148:149], v227 offset:33024
	v_mfma_f32_16x16x32_bf16 v[54:57], v[150:153], v[174:177], v[54:57]
	ds_read_b64 v[150:151], v226 offset:41216
	ds_read_b64 v[152:153], v227 offset:41216
	v_mfma_f32_16x16x32_bf16 v[58:61], v[154:157], v[174:177], v[58:61]
	ds_read_b64 v[154:155], v226 offset:49408
	ds_read_b64 v[156:157], v227 offset:49408
	v_mfma_f32_16x16x32_bf16 v[62:65], v[158:161], v[174:177], v[62:65]
	ds_read_b64 v[158:159], v226 offset:57600
	ds_read_b64 v[160:161], v227 offset:57600
	s_waitcnt lgkmcnt(15)
	v_mfma_f32_16x16x32_bf16 v[34:37], v[98:101], v[178:181], v[34:37]
	ds_read_b64 v[98:99], v228 offset:256
	ds_read_b64 v[100:101], v229 offset:256
	v_mfma_f32_16x16x32_bf16 v[38:41], v[102:105], v[178:181], v[38:41]
	ds_read_b64 v[102:103], v228 offset:8448
	ds_read_b64 v[104:105], v229 offset:8448
	v_mfma_f32_16x16x32_bf16 v[42:45], v[106:109], v[178:181], v[42:45]
	ds_read_b64 v[106:107], v228 offset:16640
	ds_read_b64 v[108:109], v229 offset:16640
	v_mfma_f32_16x16x32_bf16 v[46:49], v[110:113], v[178:181], v[46:49]
	ds_read_b64 v[110:111], v228 offset:24832
	ds_read_b64 v[112:113], v229 offset:24832
	v_mfma_f32_16x16x32_bf16 v[50:53], v[114:117], v[178:181], v[50:53]
	ds_read_b64 v[114:115], v228 offset:33024
	ds_read_b64 v[116:117], v229 offset:33024
	v_mfma_f32_16x16x32_bf16 v[54:57], v[118:121], v[178:181], v[54:57]
	ds_read_b64 v[118:119], v228 offset:41216
	ds_read_b64 v[120:121], v229 offset:41216
	v_mfma_f32_16x16x32_bf16 v[58:61], v[122:125], v[178:181], v[58:61]
	ds_read_b64 v[122:123], v228 offset:49408
	ds_read_b64 v[124:125], v229 offset:49408
	v_mfma_f32_16x16x32_bf16 v[62:65], v[126:129], v[178:181], v[62:65]
	ds_read_b64 v[126:127], v228 offset:57600
	ds_read_b64 v[128:129], v229 offset:57600
	s_waitcnt lgkmcnt(15)
; #define LAS __attribute__((address_space(3)))
; DI unsigned pk2(float lo, float hi) { const bf2_t r = __builtin_convertvector((f32x2_t){lo, hi}, bf2_t); return __builtin_bit_cast(unsigned, r); }
; #define MFMA16(a, b, c) __builtin_amdgcn_mfma_f32_16x16x32_bf16((a), (b), (c), 0, 0, 0)
; #define DSEC(k) do { if (PROBE_DSEC) { const unsigned long long tn_ = __builtin_amdgcn_s_memrealtime(); if (PROBE_DSEC == (k)) tsec += tn_ - tl_; tl_ = tn_; } } while (0)
; DI void xattn_phase(LAS unsigned char* L, const bf16* Qx, const bf16* memK, const bf16* memVT, bf16* Ox, int G, int bid, int tid, unsigned long long& tsec) {
;     ...
;             for (int pp = 0; pp < 8; ++pp)
; #pragma unroll
;                 for (int d4 = 0; d4 < 2; ++d4) { bf16x8 vf[4];
; #pragma unroll
;                     for (int dq = 0; dq < 4; ++dq) { const int dt = 4 * d4 + dq; const LAS unsigned char* vb_ = ((dt & 1) ? vod : vev) + 16 * dt * VSTR + 64 * pp;
;                         const s16x4 lo = *(const LAS s16x4*)(vb_ + (((2 * dt) & 4) << 3)), hi = *(const LAS s16x4*)(vb_ + ((((2 * dt) & 4) ^ 4) << 3)); vf[dq] = __builtin_shufflevector(lo, hi, 0, 1, 2, 3, 4, 5, 6, 7); }
; #pragma unroll
;                     for (int dq = 0; dq < 4; ++dq) o[4 * d4 + dq] = MFMA16(vf[dq], pf[pp], o[4 * d4 + dq]);
;                 }
;             { bf16* op = Ox + tq * D + h * 256 + 128 * hh + 4 * fq;
; #pragma unroll
;               for (int dt = 0; dt < 8; ++dt) *(unsigned long long*)(op + 16 * dt) = (unsigned long long)pk2(o[dt][0] * inv, o[dt][1] * inv) | ((unsigned long long)pk2(o[dt][2] * inv, o[dt][3] * inv) << 32); }
;         }
;         DSEC(14);
	v_mfma_f32_16x16x32_bf16 v[34:37], v[130:133], v[182:185], v[34:37]
	ds_read_b64 v[130:131], v230 offset:256
	ds_read_b64 v[132:133], v231 offset:256
	v_mfma_f32_16x16x32_bf16 v[38:41], v[134:137], v[182:185], v[38:41]
	ds_read_b64 v[134:135], v230 offset:8448
	ds_read_b64 v[136:137], v231 offset:8448
	v_mfma_f32_16x16x32_bf16 v[42:45], v[138:141], v[182:185], v[42:45]
	ds_read_b64 v[138:139], v230 offset:16640
	ds_read_b64 v[140:141], v231 offset:16640
	v_mfma_f32_16x16x32_bf16 v[46:49], v[142:145], v[182:185], v[46:49]
	ds_read_b64 v[142:143], v230 offset:24832
	ds_read_b64 v[144:145], v231 offset:24832
	v_mfma_f32_16x16x32_bf16 v[50:53], v[146:149], v[182:185], v[50:53]
	ds_read_b64 v[146:147], v230 offset:33024
	ds_read_b64 v[148:149], v231 offset:33024
	v_mfma_f32_16x16x32_bf16 v[54:57], v[150:153], v[182:185], v[54:57]
	ds_read_b64 v[150:151], v230 offset:41216
	ds_read_b64 v[152:153], v231 offset:41216
	v_mfma_f32_16x16x32_bf16 v[58:61], v[154:157], v[182:185], v[58:61]
	ds_read_b64 v[154:155], v230 offset:49408
	ds_read_b64 v[156:157], v231 offset:49408
	v_mfma_f32_16x16x32_bf16 v[62:65], v[158:161], v[182:185], v[62:65]
	ds_read_b64 v[158:159], v230 offset:57600
	ds_read_b64 v[160:161], v231 offset:57600
	s_waitcnt lgkmcnt(15)
	v_mfma_f32_16x16x32_bf16 v[34:37], v[98:101], v[186:189], v[34:37]
	v_mfma_f32_16x16x32_bf16 v[38:41], v[102:105], v[186:189], v[38:41]
	v_mfma_f32_16x16x32_bf16 v[42:45], v[106:109], v[186:189], v[42:45]
	v_mfma_f32_16x16x32_bf16 v[46:49], v[110:113], v[186:189], v[46:49]
	v_mfma_f32_16x16x32_bf16 v[50:53], v[114:117], v[186:189], v[50:53]
	v_mfma_f32_16x16x32_bf16 v[54:57], v[118:121], v[186:189], v[54:57]
	v_mfma_f32_16x16x32_bf16 v[58:61], v[122:125], v[186:189], v[58:61]
	v_mfma_f32_16x16x32_bf16 v[62:65], v[126:129], v[186:189], v[62:65]
	s_waitcnt lgkmcnt(0)
	v_mfma_f32_16x16x32_bf16 v[34:37], v[130:133], v[190:193], v[34:37]
	v_mfma_f32_16x16x32_bf16 v[38:41], v[134:137], v[190:193], v[38:41]
	v_mfma_f32_16x16x32_bf16 v[42:45], v[138:141], v[190:193], v[42:45]
	v_mfma_f32_16x16x32_bf16 v[46:49], v[142:145], v[190:193], v[46:49]
	v_mfma_f32_16x16x32_bf16 v[50:53], v[146:149], v[190:193], v[50:53]
	v_mfma_f32_16x16x32_bf16 v[54:57], v[150:153], v[190:193], v[54:57]
	v_mfma_f32_16x16x32_bf16 v[58:61], v[154:157], v[190:193], v[58:61]
	v_mfma_f32_16x16x32_bf16 v[62:65], v[158:161], v[190:193], v[62:65]
	v_mul_f32_e32 v2, v0, v2
	v_mul_f32_e32 v3, v0, v3
	v_mul_f32_e32 v4, v0, v4
	v_mul_f32_e32 v5, v0, v5
	v_cvt_pk_bf16_f32 v2, v2, v3
	v_cvt_pk_bf16_f32 v3, v4, v5
	global_store_dwordx2 v233, v[2:3], s[22:23]
	v_mul_f32_e32 v6, v0, v6
	v_mul_f32_e32 v7, v0, v7
	v_mul_f32_e32 v8, v0, v8
	v_mul_f32_e32 v9, v0, v9
	v_cvt_pk_bf16_f32 v6, v6, v7
	v_cvt_pk_bf16_f32 v7, v8, v9
	global_store_dwordx2 v233, v[6:7], s[22:23] offset:32
	v_mul_f32_e32 v10, v0, v10
	v_mul_f32_e32 v11, v0, v11
	v_mul_f32_e32 v12, v0, v12
	v_mul_f32_e32 v13, v0, v13
	v_cvt_pk_bf16_f32 v10, v10, v11
	v_cvt_pk_bf16_f32 v11, v12, v13
	global_store_dwordx2 v233, v[10:11], s[22:23] offset:64
	v_mul_f32_e32 v14, v0, v14
	v_mul_f32_e32 v15, v0, v15
	v_mul_f32_e32 v16, v0, v16
	v_mul_f32_e32 v17, v0, v17
	v_cvt_pk_bf16_f32 v14, v14, v15
	v_cvt_pk_bf16_f32 v15, v16, v17
	global_store_dwordx2 v233, v[14:15], s[22:23] offset:96
	v_mul_f32_e32 v18, v0, v18
	v_mul_f32_e32 v19, v0, v19
	v_mul_f32_e32 v20, v0, v20
	v_mul_f32_e32 v21, v0, v21
	v_cvt_pk_bf16_f32 v18, v18, v19
	v_cvt_pk_bf16_f32 v19, v20, v21
	global_store_dwordx2 v233, v[18:19], s[22:23] offset:128
	v_mul_f32_e32 v22, v0, v22
	v_mul_f32_e32 v23, v0, v23
	v_mul_f32_e32 v24, v0, v24
	v_mul_f32_e32 v25, v0, v25
	v_cvt_pk_bf16_f32 v22, v22, v23
	v_cvt_pk_bf16_f32 v23, v24, v25
	global_store_dwordx2 v233, v[22:23], s[22:23] offset:160
	v_mul_f32_e32 v26, v0, v26
	v_mul_f32_e32 v27, v0, v27
	v_mul_f32_e32 v28, v0, v28
	v_mul_f32_e32 v29, v0, v29
	v_cvt_pk_bf16_f32 v26, v26, v27
	v_cvt_pk_bf16_f32 v27, v28, v29
	global_store_dwordx2 v233, v[26:27], s[22:23] offset:192
	v_mul_f32_e32 v30, v0, v30
	v_mul_f32_e32 v31, v0, v31
	v_mul_f32_e32 v32, v0, v32
	v_mul_f32_e32 v33, v0, v33
	v_cvt_pk_bf16_f32 v30, v30, v31
	v_cvt_pk_bf16_f32 v31, v32, v33
	global_store_dwordx2 v233, v[30:31], s[22:23] offset:224
	v_mul_f32_e32 v34, v0, v34
	v_mul_f32_e32 v35, v0, v35
	v_mul_f32_e32 v36, v0, v36
	v_mul_f32_e32 v37, v0, v37
	v_cvt_pk_bf16_f32 v34, v34, v35
	v_cvt_pk_bf16_f32 v35, v36, v37
	global_store_dwordx2 v233, v[34:35], s[22:23] offset:256
	v_mul_f32_e32 v38, v0, v38
	v_mul_f32_e32 v39, v0, v39
	v_mul_f32_e32 v40, v0, v40
	v_mul_f32_e32 v41, v0, v41
	v_cvt_pk_bf16_f32 v38, v38, v39
	v_cvt_pk_bf16_f32 v39, v40, v41
	global_store_dwordx2 v233, v[38:39], s[22:23] offset:288
	v_mul_f32_e32 v42, v0, v42
	v_mul_f32_e32 v43, v0, v43
	v_mul_f32_e32 v44, v0, v44
	v_mul_f32_e32 v45, v0, v45
	v_cvt_pk_bf16_f32 v42, v42, v43
	v_cvt_pk_bf16_f32 v43, v44, v45
	global_store_dwordx2 v233, v[42:43], s[22:23] offset:320
	v_mul_f32_e32 v46, v0, v46
	v_mul_f32_e32 v47, v0, v47
	v_mul_f32_e32 v48, v0, v48
	v_mul_f32_e32 v49, v0, v49
	v_cvt_pk_bf16_f32 v46, v46, v47
	v_cvt_pk_bf16_f32 v47, v48, v49
	global_store_dwordx2 v233, v[46:47], s[22:23] offset:352
	v_mul_f32_e32 v50, v0, v50
	v_mul_f32_e32 v51, v0, v51
	v_mul_f32_e32 v52, v0, v52
	v_mul_f32_e32 v53, v0, v53
	v_cvt_pk_bf16_f32 v50, v50, v51
	v_cvt_pk_bf16_f32 v51, v52, v53
	global_store_dwordx2 v233, v[50:51], s[22:23] offset:384
	v_mul_f32_e32 v54, v0, v54
	v_mul_f32_e32 v55, v0, v55
	v_mul_f32_e32 v56, v0, v56
	v_mul_f32_e32 v57, v0, v57
	v_cvt_pk_bf16_f32 v54, v54, v55
	v_cvt_pk_bf16_f32 v55, v56, v57
	global_store_dwordx2 v233, v[54:55], s[22:23] offset:416
	v_mul_f32_e32 v58, v0, v58
	v_mul_f32_e32 v59, v0, v59
	v_mul_f32_e32 v60, v0, v60
	v_mul_f32_e32 v61, v0, v61
	v_cvt_pk_bf16_f32 v58, v58, v59
	v_cvt_pk_bf16_f32 v59, v60, v61
	global_store_dwordx2 v233, v[58:59], s[22:23] offset:448
	v_mul_f32_e32 v62, v0, v62
	v_mul_f32_e32 v63, v0, v63
	v_mul_f32_e32 v64, v0, v64
	v_mul_f32_e32 v65, v0, v65
	v_cvt_pk_bf16_f32 v62, v62, v63
	v_cvt_pk_bf16_f32 v63, v64, v65
	global_store_dwordx2 v233, v[62:63], s[22:23] offset:480
	s_mov_b32 s17, s18
	s_and_b32 s44, s17, 31
	s_bfe_u32 s45, s17, 0x20005
	s_lshr_b32 s46, s17, 7
	s_lshl_b32 s47, s46, 12
	s_lshl_b32 s44, s44, 7
	s_add_u32 s47, s47, s44
	s_lshl_b32 s47, s47, 11
	s_lshl_b32 s44, s45, 9
	s_add_u32 s47, s47, s44
	s_add_u32 s22, s38, s47
	s_addc_u32 s23, s39, 0
	s_waitcnt vmcnt(16)
	s_barrier
	s_branch .Lxa_loop
